# v16 with the hand-off protected by priority: incoming wave raises s_setprio only after its first MFMA pair
# baseline (speedup 1.0000x reference)
.LBB0_252:
	s_add_u32 s12, s54, 0xfff00080
	s_addc_u32 s13, s55, -1
	s_add_i32 s95, 0, 0x10000
	s_cmp_eq_u32 s94, 60
	s_cselect_b32 s65, s47, s13
	s_cselect_b32 s64, s66, s12
	s_cselect_b32 s63, s45, s61
	s_cselect_b32 s62, vcc_lo, vcc_hi
	s_add_i32 s56, 0, 0x14000
	v_add_u32_e32 v142, s95, v144
	ds_read_b128 v[148:151], v142
	ds_read_b128 v[152:155], v142 offset:1024
	ds_read_b128 v[156:159], v142 offset:2048
	ds_read_b128 v[160:163], v142 offset:3072
	v_add_u32_e32 v142, s56, v144
	ds_read_b128 v[164:167], v142
	ds_read_b128 v[168:171], v142 offset:1024
	ds_read_b128 v[172:175], v142 offset:2048
	ds_read_b128 v[176:179], v142 offset:3072
	ds_read_b128 v[180:183], v146
	ds_read_b128 v[184:187], v146 offset:1024
	ds_read_b128 v[210:213], v146 offset:2048
	ds_read_b128 v[214:217], v146 offset:3072
	ds_read_b128 v[218:221], v146 offset:4096
	ds_read_b128 v[222:225], v146 offset:5120
	ds_read_b128 v[226:229], v146 offset:6144
	ds_read_b128 v[230:233], v146 offset:7168
	s_add_i32 m0, s53, 0xc000
	s_nop 0
	global_load_lds_dwordx4 v136, s[54:55]
	s_add_i32 m0, s53, 0xe000
	s_nop 0
	global_load_lds_dwordx4 v138, s[54:55]
	s_waitcnt vmcnt(8)
	s_waitcnt lgkmcnt(0)
	s_barrier
	s_waitcnt lgkmcnt(0)
	v_mfma_f32_16x16x32_bf16 v[126:129], v[148:151], v[180:183], v[126:129]
	v_mfma_f32_16x16x32_bf16 v[126:129], v[152:155], v[184:187], v[126:129]
	s_setprio 1
	v_mfma_f32_16x16x32_bf16 v[114:117], v[152:155], v[214:217], v[114:117]
	v_mfma_f32_16x16x32_bf16 v[114:117], v[148:151], v[210:213], v[114:117]
	v_mfma_f32_16x16x32_bf16 v[98:101], v[148:151], v[218:221], v[98:101]
	v_mfma_f32_16x16x32_bf16 v[98:101], v[152:155], v[222:225], v[98:101]
	v_mfma_f32_16x16x32_bf16 v[82:85], v[152:155], v[230:233], v[82:85]
	v_mfma_f32_16x16x32_bf16 v[82:85], v[148:151], v[226:229], v[82:85]
	v_mfma_f32_16x16x32_bf16 v[74:77], v[156:159], v[226:229], v[74:77]
	v_mfma_f32_16x16x32_bf16 v[74:77], v[160:163], v[230:233], v[74:77]
	v_mfma_f32_16x16x32_bf16 v[90:93], v[160:163], v[222:225], v[90:93]
	v_mfma_f32_16x16x32_bf16 v[90:93], v[156:159], v[218:221], v[90:93]
	v_mfma_f32_16x16x32_bf16 v[106:109], v[156:159], v[210:213], v[106:109]
	v_mfma_f32_16x16x32_bf16 v[106:109], v[160:163], v[214:217], v[106:109]
	v_mfma_f32_16x16x32_bf16 v[122:125], v[160:163], v[184:187], v[122:125]
	v_mfma_f32_16x16x32_bf16 v[122:125], v[156:159], v[180:183], v[122:125]
	v_mfma_f32_16x16x32_bf16 v[110:113], v[172:175], v[180:183], v[110:113]
	v_mfma_f32_16x16x32_bf16 v[110:113], v[176:179], v[184:187], v[110:113]
	v_mfma_f32_16x16x32_bf16 v[94:97], v[176:179], v[214:217], v[94:97]
	v_mfma_f32_16x16x32_bf16 v[94:97], v[172:175], v[210:213], v[94:97]
	v_mfma_f32_16x16x32_bf16 v[78:81], v[172:175], v[218:221], v[78:81]
	v_mfma_f32_16x16x32_bf16 v[78:81], v[176:179], v[222:225], v[78:81]
	v_mfma_f32_16x16x32_bf16 v[66:69], v[176:179], v[230:233], v[66:69]
	v_mfma_f32_16x16x32_bf16 v[66:69], v[172:175], v[226:229], v[66:69]
	v_mfma_f32_16x16x32_bf16 v[70:73], v[164:167], v[226:229], v[70:73]
	v_mfma_f32_16x16x32_bf16 v[70:73], v[168:171], v[230:233], v[70:73]
	v_mfma_f32_16x16x32_bf16 v[86:89], v[168:171], v[222:225], v[86:89]
	v_mfma_f32_16x16x32_bf16 v[86:89], v[164:167], v[218:221], v[86:89]
	v_mfma_f32_16x16x32_bf16 v[102:105], v[164:167], v[210:213], v[102:105]
	v_mfma_f32_16x16x32_bf16 v[102:105], v[168:171], v[214:217], v[102:105]
	v_mfma_f32_16x16x32_bf16 v[118:121], v[168:171], v[184:187], v[118:121]
	s_barrier
	v_mfma_f32_16x16x32_bf16 v[118:121], v[164:167], v[180:183], v[118:121]
	s_setprio 0
	s_add_i32 s12, s95, s82
	ds_read_b128 v[180:183], v146 offset:16384
	ds_read_b128 v[184:187], v146 offset:17408
	ds_read_b128 v[210:213], v146 offset:18432
	ds_read_b128 v[214:217], v146 offset:19456
	ds_read_b128 v[218:221], v146 offset:20480
	ds_read_b128 v[222:225], v146 offset:21504
	ds_read_b128 v[226:229], v146 offset:22528
	ds_read_b128 v[230:233], v146 offset:23552
	s_mov_b32 m0, s12
	s_nop 0
	global_load_lds_dwordx4 v190, s[62:63]
	s_add_i32 m0, s12, 0x2000
	s_add_u32 s12, s62, 0x100000
	s_addc_u32 s13, s63, 0
	s_add_i32 s56, s56, s82
	global_load_lds_dwordx4 v134, s[62:63]
	s_mov_b32 m0, s56
	s_nop 0
	global_load_lds_dwordx4 v190, s[12:13]
	s_add_i32 m0, s56, 0x2000
	s_nop 0
	global_load_lds_dwordx4 v134, s[12:13]
	s_mov_b32 m0, s53
	s_nop 0
	global_load_lds_dwordx4 v130, s[64:65]
	s_mov_b32 m0, s84
	s_nop 0
	global_load_lds_dwordx4 v132, s[64:65]
	s_waitcnt vmcnt(8)
	s_waitcnt lgkmcnt(0)
	s_barrier
	s_waitcnt lgkmcnt(0)
	v_mfma_f32_16x16x32_bf16 v[62:65], v[148:151], v[180:183], v[62:65]
	v_mfma_f32_16x16x32_bf16 v[62:65], v[152:155], v[184:187], v[62:65]
	s_setprio 1
	v_mfma_f32_16x16x32_bf16 v[50:53], v[152:155], v[214:217], v[50:53]
	v_mfma_f32_16x16x32_bf16 v[50:53], v[148:151], v[210:213], v[50:53]
	v_mfma_f32_16x16x32_bf16 v[34:37], v[148:151], v[218:221], v[34:37]
	v_mfma_f32_16x16x32_bf16 v[34:37], v[152:155], v[222:225], v[34:37]
	v_mfma_f32_16x16x32_bf16 v[18:21], v[152:155], v[230:233], v[18:21]
	v_mfma_f32_16x16x32_bf16 v[18:21], v[148:151], v[226:229], v[18:21]
	v_mfma_f32_16x16x32_bf16 v[10:13], v[156:159], v[226:229], v[10:13]
	v_mfma_f32_16x16x32_bf16 v[10:13], v[160:163], v[230:233], v[10:13]
	v_mfma_f32_16x16x32_bf16 v[26:29], v[160:163], v[222:225], v[26:29]
	v_mfma_f32_16x16x32_bf16 v[26:29], v[156:159], v[218:221], v[26:29]
	v_mfma_f32_16x16x32_bf16 v[42:45], v[156:159], v[210:213], v[42:45]
	v_mfma_f32_16x16x32_bf16 v[42:45], v[160:163], v[214:217], v[42:45]
	v_mfma_f32_16x16x32_bf16 v[58:61], v[160:163], v[184:187], v[58:61]
	v_mfma_f32_16x16x32_bf16 v[58:61], v[156:159], v[180:183], v[58:61]
	v_mfma_f32_16x16x32_bf16 v[46:49], v[172:175], v[180:183], v[46:49]
	v_mfma_f32_16x16x32_bf16 v[46:49], v[176:179], v[184:187], v[46:49]
	v_mfma_f32_16x16x32_bf16 v[30:33], v[176:179], v[214:217], v[30:33]
	v_mfma_f32_16x16x32_bf16 v[30:33], v[172:175], v[210:213], v[30:33]
	v_mfma_f32_16x16x32_bf16 v[14:17], v[172:175], v[218:221], v[14:17]
	v_mfma_f32_16x16x32_bf16 v[14:17], v[176:179], v[222:225], v[14:17]
	v_mfma_f32_16x16x32_bf16 v[2:5], v[176:179], v[230:233], v[2:5]
	v_mfma_f32_16x16x32_bf16 v[2:5], v[172:175], v[226:229], v[2:5]
	v_mfma_f32_16x16x32_bf16 v[6:9], v[164:167], v[226:229], v[6:9]
	v_mfma_f32_16x16x32_bf16 v[6:9], v[168:171], v[230:233], v[6:9]
	v_mfma_f32_16x16x32_bf16 v[22:25], v[168:171], v[222:225], v[22:25]
	v_mfma_f32_16x16x32_bf16 v[22:25], v[164:167], v[218:221], v[22:25]
	v_mfma_f32_16x16x32_bf16 v[38:41], v[164:167], v[210:213], v[38:41]
	v_mfma_f32_16x16x32_bf16 v[38:41], v[168:171], v[214:217], v[38:41]
	v_mfma_f32_16x16x32_bf16 v[54:57], v[168:171], v[184:187], v[54:57]
	s_barrier
	v_mfma_f32_16x16x32_bf16 v[54:57], v[164:167], v[180:183], v[54:57]
	s_setprio 0
	s_add_i32 s56, 0, 0x18000
	s_add_i32 s95, 0, 0x1c000
	s_add_u32 s12, s64, 0x100000
	s_addc_u32 s13, s65, 0
	v_add_u32_e32 v147, s56, v144
	ds_read_b128 v[148:151], v147
	ds_read_b128 v[152:155], v147 offset:1024
	ds_read_b128 v[156:159], v147 offset:2048
	ds_read_b128 v[160:163], v147 offset:3072
	v_add_u32_e32 v147, s95, v144
	ds_read_b128 v[164:167], v147
	ds_read_b128 v[168:171], v147 offset:1024
	ds_read_b128 v[172:175], v147 offset:2048
	ds_read_b128 v[176:179], v147 offset:3072
	ds_read_b128 v[180:183], v146 offset:32768
	ds_read_b128 v[184:187], v146 offset:33792
	ds_read_b128 v[210:213], v146 offset:34816
	ds_read_b128 v[214:217], v146 offset:35840
	ds_read_b128 v[218:221], v146 offset:36864
	ds_read_b128 v[222:225], v146 offset:37888
	ds_read_b128 v[226:229], v146 offset:38912
	ds_read_b128 v[230:233], v146 offset:39936
	s_mov_b32 m0, s85
	s_nop 0
	global_load_lds_dwordx4 v130, s[12:13]
	s_mov_b32 m0, s86
	s_nop 0
	global_load_lds_dwordx4 v132, s[12:13]
	s_waitcnt vmcnt(8)
	s_waitcnt lgkmcnt(0)
	s_barrier
	s_waitcnt lgkmcnt(0)
	v_mfma_f32_16x16x32_bf16 v[126:129], v[148:151], v[180:183], v[126:129]
	v_mfma_f32_16x16x32_bf16 v[126:129], v[152:155], v[184:187], v[126:129]
	s_setprio 1
	v_mfma_f32_16x16x32_bf16 v[114:117], v[152:155], v[214:217], v[114:117]
	v_mfma_f32_16x16x32_bf16 v[114:117], v[148:151], v[210:213], v[114:117]
	v_mfma_f32_16x16x32_bf16 v[98:101], v[148:151], v[218:221], v[98:101]
	v_mfma_f32_16x16x32_bf16 v[98:101], v[152:155], v[222:225], v[98:101]
	v_mfma_f32_16x16x32_bf16 v[82:85], v[152:155], v[230:233], v[82:85]
	v_mfma_f32_16x16x32_bf16 v[82:85], v[148:151], v[226:229], v[82:85]
	v_mfma_f32_16x16x32_bf16 v[74:77], v[156:159], v[226:229], v[74:77]
	v_mfma_f32_16x16x32_bf16 v[74:77], v[160:163], v[230:233], v[74:77]
	v_mfma_f32_16x16x32_bf16 v[90:93], v[160:163], v[222:225], v[90:93]
	v_mfma_f32_16x16x32_bf16 v[90:93], v[156:159], v[218:221], v[90:93]
	v_mfma_f32_16x16x32_bf16 v[106:109], v[156:159], v[210:213], v[106:109]
	v_mfma_f32_16x16x32_bf16 v[106:109], v[160:163], v[214:217], v[106:109]
	v_mfma_f32_16x16x32_bf16 v[122:125], v[160:163], v[184:187], v[122:125]
	v_mfma_f32_16x16x32_bf16 v[122:125], v[156:159], v[180:183], v[122:125]
	v_mfma_f32_16x16x32_bf16 v[110:113], v[172:175], v[180:183], v[110:113]
	v_mfma_f32_16x16x32_bf16 v[110:113], v[176:179], v[184:187], v[110:113]
	v_mfma_f32_16x16x32_bf16 v[94:97], v[176:179], v[214:217], v[94:97]
	v_mfma_f32_16x16x32_bf16 v[94:97], v[172:175], v[210:213], v[94:97]
	v_mfma_f32_16x16x32_bf16 v[78:81], v[172:175], v[218:221], v[78:81]
	v_mfma_f32_16x16x32_bf16 v[78:81], v[176:179], v[222:225], v[78:81]
	v_mfma_f32_16x16x32_bf16 v[66:69], v[176:179], v[230:233], v[66:69]
	v_mfma_f32_16x16x32_bf16 v[66:69], v[172:175], v[226:229], v[66:69]
	v_mfma_f32_16x16x32_bf16 v[70:73], v[164:167], v[226:229], v[70:73]
	v_mfma_f32_16x16x32_bf16 v[70:73], v[168:171], v[230:233], v[70:73]
	v_mfma_f32_16x16x32_bf16 v[86:89], v[168:171], v[222:225], v[86:89]
	v_mfma_f32_16x16x32_bf16 v[86:89], v[164:167], v[218:221], v[86:89]
	v_mfma_f32_16x16x32_bf16 v[102:105], v[164:167], v[210:213], v[102:105]
	v_mfma_f32_16x16x32_bf16 v[102:105], v[168:171], v[214:217], v[102:105]
	v_mfma_f32_16x16x32_bf16 v[118:121], v[168:171], v[184:187], v[118:121]
	s_barrier
	v_mfma_f32_16x16x32_bf16 v[118:121], v[164:167], v[180:183], v[118:121]
	s_setprio 0
	s_add_i32 s12, s56, s82
	ds_read_b128 v[180:183], v146 offset:49152
	ds_read_b128 v[184:187], v146 offset:50176
	ds_read_b128 v[210:213], v146 offset:51200
	ds_read_b128 v[214:217], v146 offset:52224
	ds_read_b128 v[218:221], v146 offset:53248
	ds_read_b128 v[222:225], v146 offset:54272
	ds_read_b128 v[226:229], v146 offset:55296
	ds_read_b128 v[230:233], v146 offset:56320
	s_mov_b32 m0, s12
	s_nop 0
	global_load_lds_dwordx4 v234, s[62:63]
	s_add_i32 m0, s12, 0x2000
	s_add_u32 s12, s62, 0x100080
	s_addc_u32 s13, s63, 0
	s_add_i32 s56, s95, s82
	global_load_lds_dwordx4 v189, s[62:63]
	s_mov_b32 m0, s56
	s_nop 0
	global_load_lds_dwordx4 v190, s[12:13]
	s_add_i32 m0, s56, 0x2000
	s_nop 0
	global_load_lds_dwordx4 v134, s[12:13]
	s_mov_b32 m0, s90
	s_nop 0
	global_load_lds_dwordx4 v143, s[64:65]
	s_mov_b32 m0, s97
	s_nop 0
	global_load_lds_dwordx4 v188, s[64:65]
	s_waitcnt vmcnt(8)
	s_waitcnt lgkmcnt(0)
	s_barrier
	s_waitcnt lgkmcnt(0)
	v_mfma_f32_16x16x32_bf16 v[62:65], v[148:151], v[180:183], v[62:65]
	v_mfma_f32_16x16x32_bf16 v[62:65], v[152:155], v[184:187], v[62:65]
	s_setprio 1
	v_mfma_f32_16x16x32_bf16 v[50:53], v[152:155], v[214:217], v[50:53]
	v_mfma_f32_16x16x32_bf16 v[50:53], v[148:151], v[210:213], v[50:53]
	v_mfma_f32_16x16x32_bf16 v[34:37], v[148:151], v[218:221], v[34:37]
	v_mfma_f32_16x16x32_bf16 v[34:37], v[152:155], v[222:225], v[34:37]
	v_mfma_f32_16x16x32_bf16 v[18:21], v[152:155], v[230:233], v[18:21]
	v_mfma_f32_16x16x32_bf16 v[18:21], v[148:151], v[226:229], v[18:21]
	v_mfma_f32_16x16x32_bf16 v[10:13], v[156:159], v[226:229], v[10:13]
	v_mfma_f32_16x16x32_bf16 v[10:13], v[160:163], v[230:233], v[10:13]
	v_mfma_f32_16x16x32_bf16 v[26:29], v[160:163], v[222:225], v[26:29]
	v_mfma_f32_16x16x32_bf16 v[26:29], v[156:159], v[218:221], v[26:29]
	v_mfma_f32_16x16x32_bf16 v[42:45], v[156:159], v[210:213], v[42:45]
	v_mfma_f32_16x16x32_bf16 v[42:45], v[160:163], v[214:217], v[42:45]
	v_mfma_f32_16x16x32_bf16 v[58:61], v[160:163], v[184:187], v[58:61]
	v_mfma_f32_16x16x32_bf16 v[58:61], v[156:159], v[180:183], v[58:61]
	v_mfma_f32_16x16x32_bf16 v[46:49], v[172:175], v[180:183], v[46:49]
	v_mfma_f32_16x16x32_bf16 v[46:49], v[176:179], v[184:187], v[46:49]
	v_mfma_f32_16x16x32_bf16 v[30:33], v[176:179], v[214:217], v[30:33]
	v_mfma_f32_16x16x32_bf16 v[30:33], v[172:175], v[210:213], v[30:33]
	v_mfma_f32_16x16x32_bf16 v[14:17], v[172:175], v[218:221], v[14:17]
	v_mfma_f32_16x16x32_bf16 v[14:17], v[176:179], v[222:225], v[14:17]
	v_mfma_f32_16x16x32_bf16 v[2:5], v[176:179], v[230:233], v[2:5]
	v_mfma_f32_16x16x32_bf16 v[2:5], v[172:175], v[226:229], v[2:5]
	v_mfma_f32_16x16x32_bf16 v[6:9], v[164:167], v[226:229], v[6:9]
	v_mfma_f32_16x16x32_bf16 v[6:9], v[168:171], v[230:233], v[6:9]
	v_mfma_f32_16x16x32_bf16 v[22:25], v[168:171], v[222:225], v[22:25]
	v_mfma_f32_16x16x32_bf16 v[22:25], v[164:167], v[218:221], v[22:25]
	v_mfma_f32_16x16x32_bf16 v[38:41], v[164:167], v[210:213], v[38:41]
	v_mfma_f32_16x16x32_bf16 v[38:41], v[168:171], v[214:217], v[38:41]
	v_mfma_f32_16x16x32_bf16 v[54:57], v[168:171], v[184:187], v[54:57]
	s_barrier
	v_mfma_f32_16x16x32_bf16 v[54:57], v[164:167], v[180:183], v[54:57]
	s_setprio 0
	s_add_i32 s94, s94, 2
	s_add_u32 s54, s54, 0x100
	s_addc_u32 s55, s55, 0
	s_add_u32 vcc_hi, vcc_hi, 0x100
	s_addc_u32 s61, s61, 0
	s_cmp_gt_u32 s94, 61
	s_cbranch_scc0 .LBB0_252
	s_and_b64 vcc, exec, s[42:43]
	s_cbranch_vccz .LBB0_255
	s_barrier

.LBB0_692:
	s_add_u32 s12, s40, 0xfffc0080
	s_addc_u32 s13, s41, -1
	s_add_i32 s56, 0, 0x10000
	s_cmp_eq_u32 s74, 12
	s_cselect_b32 s63, s47, s13
	s_cselect_b32 s62, s71, s12
	s_cselect_b32 s55, s45, s61
	s_cselect_b32 s54, s72, s73
	s_add_i32 s75, 0, 0x14000
	v_add_u32_e32 v142, s56, v160
	v_add_u32_e32 v163, s75, v160
	ds_read_b128 v[130:133], v142
	ds_read_b128 v[134:137], v142 offset:1024
	ds_read_b128 v[138:141], v142 offset:2048
	ds_read_b128 v[142:145], v142 offset:3072
	ds_read_b128 v[156:159], v163
	ds_read_b128 v[164:167], v163 offset:1024
	ds_read_b128 v[168:171], v163 offset:2048
	ds_read_b128 v[172:175], v163 offset:3072
	ds_read_b128 v[176:179], v162
	ds_read_b128 v[180:183], v162 offset:1024
	ds_read_b128 v[184:187], v162 offset:2048
	ds_read_b128 v[210:213], v162 offset:3072
	ds_read_b128 v[214:217], v162 offset:4096
	ds_read_b128 v[218:221], v162 offset:5120
	ds_read_b128 v[222:225], v162 offset:6144
	ds_read_b128 v[226:229], v162 offset:7168
	s_add_i32 m0, s53, 0xc000
	s_nop 0
	global_load_lds_dwordx4 v152, s[40:41]
	s_add_i32 m0, s53, 0xe000
	s_nop 0
	global_load_lds_dwordx4 v154, s[40:41]
	s_waitcnt vmcnt(8)
	s_waitcnt lgkmcnt(0)
	s_barrier
	s_waitcnt lgkmcnt(0)
	v_mfma_f32_16x16x32_bf16 v[126:129], v[130:133], v[176:179], v[126:129]
	v_mfma_f32_16x16x32_bf16 v[126:129], v[134:137], v[180:183], v[126:129]
	s_setprio 1
	v_mfma_f32_16x16x32_bf16 v[114:117], v[134:137], v[210:213], v[114:117]
	v_mfma_f32_16x16x32_bf16 v[114:117], v[130:133], v[184:187], v[114:117]
	v_mfma_f32_16x16x32_bf16 v[98:101], v[130:133], v[214:217], v[98:101]
	v_mfma_f32_16x16x32_bf16 v[98:101], v[134:137], v[218:221], v[98:101]
	v_mfma_f32_16x16x32_bf16 v[82:85], v[134:137], v[226:229], v[82:85]
	v_mfma_f32_16x16x32_bf16 v[82:85], v[130:133], v[222:225], v[82:85]
	v_mfma_f32_16x16x32_bf16 v[74:77], v[138:141], v[222:225], v[74:77]
	v_mfma_f32_16x16x32_bf16 v[74:77], v[142:145], v[226:229], v[74:77]
	v_mfma_f32_16x16x32_bf16 v[90:93], v[142:145], v[218:221], v[90:93]
	v_mfma_f32_16x16x32_bf16 v[90:93], v[138:141], v[214:217], v[90:93]
	v_mfma_f32_16x16x32_bf16 v[106:109], v[138:141], v[184:187], v[106:109]
	v_mfma_f32_16x16x32_bf16 v[106:109], v[142:145], v[210:213], v[106:109]
	v_mfma_f32_16x16x32_bf16 v[122:125], v[142:145], v[180:183], v[122:125]
	v_mfma_f32_16x16x32_bf16 v[122:125], v[138:141], v[176:179], v[122:125]
	v_mfma_f32_16x16x32_bf16 v[110:113], v[168:171], v[176:179], v[110:113]
	v_mfma_f32_16x16x32_bf16 v[110:113], v[172:175], v[180:183], v[110:113]
	v_mfma_f32_16x16x32_bf16 v[94:97], v[172:175], v[210:213], v[94:97]
	v_mfma_f32_16x16x32_bf16 v[94:97], v[168:171], v[184:187], v[94:97]
	v_mfma_f32_16x16x32_bf16 v[78:81], v[168:171], v[214:217], v[78:81]
	v_mfma_f32_16x16x32_bf16 v[78:81], v[172:175], v[218:221], v[78:81]
	v_mfma_f32_16x16x32_bf16 v[66:69], v[172:175], v[226:229], v[66:69]
	v_mfma_f32_16x16x32_bf16 v[66:69], v[168:171], v[222:225], v[66:69]
	v_mfma_f32_16x16x32_bf16 v[70:73], v[156:159], v[222:225], v[70:73]
	v_mfma_f32_16x16x32_bf16 v[70:73], v[164:167], v[226:229], v[70:73]
	v_mfma_f32_16x16x32_bf16 v[86:89], v[164:167], v[218:221], v[86:89]
	v_mfma_f32_16x16x32_bf16 v[86:89], v[156:159], v[214:217], v[86:89]
	v_mfma_f32_16x16x32_bf16 v[102:105], v[156:159], v[184:187], v[102:105]
	v_mfma_f32_16x16x32_bf16 v[102:105], v[164:167], v[210:213], v[102:105]
	v_mfma_f32_16x16x32_bf16 v[118:121], v[164:167], v[180:183], v[118:121]
	s_barrier
	v_mfma_f32_16x16x32_bf16 v[118:121], v[156:159], v[176:179], v[118:121]
	s_setprio 0
	s_add_i32 s12, s56, s59
	ds_read_b128 v[176:179], v162 offset:16384
	ds_read_b128 v[180:183], v162 offset:17408
	ds_read_b128 v[184:187], v162 offset:18432
	ds_read_b128 v[210:213], v162 offset:19456
	ds_read_b128 v[214:217], v162 offset:20480
	ds_read_b128 v[218:221], v162 offset:21504
	ds_read_b128 v[222:225], v162 offset:22528
	ds_read_b128 v[226:229], v162 offset:23552
	s_mov_b32 m0, s12
	s_nop 0
	global_load_lds_dwordx4 v190, s[54:55]
	s_add_i32 m0, s12, 0x2000
	s_add_u32 s12, s54, 0x40000
	s_addc_u32 s13, s55, 0
	s_add_i32 s56, s75, s59
	global_load_lds_dwordx4 v150, s[54:55]
	s_mov_b32 m0, s56
	s_nop 0
	global_load_lds_dwordx4 v190, s[12:13]
	s_add_i32 m0, s56, 0x2000
	s_nop 0
	global_load_lds_dwordx4 v150, s[12:13]
	s_mov_b32 m0, s53
	s_nop 0
	global_load_lds_dwordx4 v146, s[62:63]
	s_mov_b32 m0, s60
	s_nop 0
	global_load_lds_dwordx4 v148, s[62:63]
	s_waitcnt vmcnt(8)
	s_waitcnt lgkmcnt(0)
	s_barrier
	s_waitcnt lgkmcnt(0)
	v_mfma_f32_16x16x32_bf16 v[62:65], v[130:133], v[176:179], v[62:65]
	v_mfma_f32_16x16x32_bf16 v[62:65], v[134:137], v[180:183], v[62:65]
	s_setprio 1
	v_mfma_f32_16x16x32_bf16 v[50:53], v[134:137], v[210:213], v[50:53]
	v_mfma_f32_16x16x32_bf16 v[50:53], v[130:133], v[184:187], v[50:53]
	v_mfma_f32_16x16x32_bf16 v[34:37], v[130:133], v[214:217], v[34:37]
	v_mfma_f32_16x16x32_bf16 v[34:37], v[134:137], v[218:221], v[34:37]
	v_mfma_f32_16x16x32_bf16 v[18:21], v[134:137], v[226:229], v[18:21]
	v_mfma_f32_16x16x32_bf16 v[18:21], v[130:133], v[222:225], v[18:21]
	v_mfma_f32_16x16x32_bf16 v[10:13], v[138:141], v[222:225], v[10:13]
	v_mfma_f32_16x16x32_bf16 v[10:13], v[142:145], v[226:229], v[10:13]
	v_mfma_f32_16x16x32_bf16 v[26:29], v[142:145], v[218:221], v[26:29]
	v_mfma_f32_16x16x32_bf16 v[26:29], v[138:141], v[214:217], v[26:29]
	v_mfma_f32_16x16x32_bf16 v[42:45], v[138:141], v[184:187], v[42:45]
	v_mfma_f32_16x16x32_bf16 v[42:45], v[142:145], v[210:213], v[42:45]
	v_mfma_f32_16x16x32_bf16 v[58:61], v[142:145], v[180:183], v[58:61]
	v_mfma_f32_16x16x32_bf16 v[58:61], v[138:141], v[176:179], v[58:61]
	v_mfma_f32_16x16x32_bf16 v[46:49], v[168:171], v[176:179], v[46:49]
	v_mfma_f32_16x16x32_bf16 v[46:49], v[172:175], v[180:183], v[46:49]
	v_mfma_f32_16x16x32_bf16 v[30:33], v[172:175], v[210:213], v[30:33]
	v_mfma_f32_16x16x32_bf16 v[30:33], v[168:171], v[184:187], v[30:33]
	v_mfma_f32_16x16x32_bf16 v[14:17], v[168:171], v[214:217], v[14:17]
	v_mfma_f32_16x16x32_bf16 v[14:17], v[172:175], v[218:221], v[14:17]
	v_mfma_f32_16x16x32_bf16 v[2:5], v[172:175], v[226:229], v[2:5]
	v_mfma_f32_16x16x32_bf16 v[2:5], v[168:171], v[222:225], v[2:5]
	v_mfma_f32_16x16x32_bf16 v[6:9], v[156:159], v[222:225], v[6:9]
	v_mfma_f32_16x16x32_bf16 v[6:9], v[164:167], v[226:229], v[6:9]
	v_mfma_f32_16x16x32_bf16 v[22:25], v[164:167], v[218:221], v[22:25]
	v_mfma_f32_16x16x32_bf16 v[22:25], v[156:159], v[214:217], v[22:25]
	v_mfma_f32_16x16x32_bf16 v[38:41], v[156:159], v[184:187], v[38:41]
	v_mfma_f32_16x16x32_bf16 v[38:41], v[164:167], v[210:213], v[38:41]
	v_mfma_f32_16x16x32_bf16 v[54:57], v[164:167], v[180:183], v[54:57]
	s_barrier
	v_mfma_f32_16x16x32_bf16 v[54:57], v[156:159], v[176:179], v[54:57]
	s_setprio 0
	s_add_i32 s56, 0, 0x18000
	s_add_i32 s75, 0, 0x1c000
	s_add_u32 s12, s62, 0x40000
	s_addc_u32 s13, s63, 0
	v_add_u32_e32 v142, s56, v160
	v_add_u32_e32 v163, s75, v160
	ds_read_b128 v[130:133], v142
	ds_read_b128 v[134:137], v142 offset:1024
	ds_read_b128 v[138:141], v142 offset:2048
	ds_read_b128 v[142:145], v142 offset:3072
	ds_read_b128 v[156:159], v163
	ds_read_b128 v[164:167], v163 offset:1024
	ds_read_b128 v[168:171], v163 offset:2048
	ds_read_b128 v[172:175], v163 offset:3072
	ds_read_b128 v[176:179], v162 offset:32768
	ds_read_b128 v[180:183], v162 offset:33792
	ds_read_b128 v[184:187], v162 offset:34816
	ds_read_b128 v[210:213], v162 offset:35840
	ds_read_b128 v[214:217], v162 offset:36864
	ds_read_b128 v[218:221], v162 offset:37888
	ds_read_b128 v[222:225], v162 offset:38912
	ds_read_b128 v[226:229], v162 offset:39936
	s_mov_b32 m0, s64
	s_nop 0
	global_load_lds_dwordx4 v146, s[12:13]
	s_mov_b32 m0, s65
	s_nop 0
	global_load_lds_dwordx4 v148, s[12:13]
	s_waitcnt vmcnt(8)
	s_waitcnt lgkmcnt(0)
	s_barrier
	s_waitcnt lgkmcnt(0)
	v_mfma_f32_16x16x32_bf16 v[126:129], v[130:133], v[176:179], v[126:129]
	v_mfma_f32_16x16x32_bf16 v[126:129], v[134:137], v[180:183], v[126:129]
	s_setprio 1
	v_mfma_f32_16x16x32_bf16 v[114:117], v[134:137], v[210:213], v[114:117]
	v_mfma_f32_16x16x32_bf16 v[114:117], v[130:133], v[184:187], v[114:117]
	v_mfma_f32_16x16x32_bf16 v[98:101], v[130:133], v[214:217], v[98:101]
	v_mfma_f32_16x16x32_bf16 v[98:101], v[134:137], v[218:221], v[98:101]
	v_mfma_f32_16x16x32_bf16 v[82:85], v[134:137], v[226:229], v[82:85]
	v_mfma_f32_16x16x32_bf16 v[82:85], v[130:133], v[222:225], v[82:85]
	v_mfma_f32_16x16x32_bf16 v[74:77], v[138:141], v[222:225], v[74:77]
	v_mfma_f32_16x16x32_bf16 v[74:77], v[142:145], v[226:229], v[74:77]
	v_mfma_f32_16x16x32_bf16 v[90:93], v[142:145], v[218:221], v[90:93]
	v_mfma_f32_16x16x32_bf16 v[90:93], v[138:141], v[214:217], v[90:93]
	v_mfma_f32_16x16x32_bf16 v[106:109], v[138:141], v[184:187], v[106:109]
	v_mfma_f32_16x16x32_bf16 v[106:109], v[142:145], v[210:213], v[106:109]
	v_mfma_f32_16x16x32_bf16 v[122:125], v[142:145], v[180:183], v[122:125]
	v_mfma_f32_16x16x32_bf16 v[122:125], v[138:141], v[176:179], v[122:125]
	v_mfma_f32_16x16x32_bf16 v[110:113], v[168:171], v[176:179], v[110:113]
	v_mfma_f32_16x16x32_bf16 v[110:113], v[172:175], v[180:183], v[110:113]
	v_mfma_f32_16x16x32_bf16 v[94:97], v[172:175], v[210:213], v[94:97]
	v_mfma_f32_16x16x32_bf16 v[94:97], v[168:171], v[184:187], v[94:97]
	v_mfma_f32_16x16x32_bf16 v[78:81], v[168:171], v[214:217], v[78:81]
	v_mfma_f32_16x16x32_bf16 v[78:81], v[172:175], v[218:221], v[78:81]
	v_mfma_f32_16x16x32_bf16 v[66:69], v[172:175], v[226:229], v[66:69]
	v_mfma_f32_16x16x32_bf16 v[66:69], v[168:171], v[222:225], v[66:69]
	v_mfma_f32_16x16x32_bf16 v[70:73], v[156:159], v[222:225], v[70:73]
	v_mfma_f32_16x16x32_bf16 v[70:73], v[164:167], v[226:229], v[70:73]
	v_mfma_f32_16x16x32_bf16 v[86:89], v[164:167], v[218:221], v[86:89]
	v_mfma_f32_16x16x32_bf16 v[86:89], v[156:159], v[214:217], v[86:89]
	v_mfma_f32_16x16x32_bf16 v[102:105], v[156:159], v[184:187], v[102:105]
	v_mfma_f32_16x16x32_bf16 v[102:105], v[164:167], v[210:213], v[102:105]
	v_mfma_f32_16x16x32_bf16 v[118:121], v[164:167], v[180:183], v[118:121]
	s_barrier
	v_mfma_f32_16x16x32_bf16 v[118:121], v[156:159], v[176:179], v[118:121]
	s_setprio 0
	s_add_i32 s12, s56, s59
	ds_read_b128 v[176:179], v162 offset:49152
	ds_read_b128 v[180:183], v162 offset:50176
	ds_read_b128 v[184:187], v162 offset:51200
	ds_read_b128 v[210:213], v162 offset:52224
	ds_read_b128 v[214:217], v162 offset:53248
	ds_read_b128 v[218:221], v162 offset:54272
	ds_read_b128 v[222:225], v162 offset:55296
	ds_read_b128 v[226:229], v162 offset:56320
	s_mov_b32 m0, s12
	s_nop 0
	global_load_lds_dwordx4 v231, s[54:55]
	s_add_i32 m0, s12, 0x2000
	s_add_u32 s12, s54, 0x40080
	s_addc_u32 s13, s55, 0
	global_load_lds_dwordx4 v230, s[54:55]
	s_add_i32 s54, s75, s59
	s_mov_b32 m0, s54
	s_nop 0
	global_load_lds_dwordx4 v190, s[12:13]
	s_add_i32 m0, s54, 0x2000
	s_nop 0
	global_load_lds_dwordx4 v150, s[12:13]
	s_mov_b32 m0, s66
	s_nop 0
	global_load_lds_dwordx4 v188, s[62:63]
	s_mov_b32 m0, s68
	s_nop 0
	global_load_lds_dwordx4 v189, s[62:63]
	s_waitcnt vmcnt(8)
	s_waitcnt lgkmcnt(0)
	s_barrier
	s_waitcnt lgkmcnt(0)
	v_mfma_f32_16x16x32_bf16 v[62:65], v[130:133], v[176:179], v[62:65]
	v_mfma_f32_16x16x32_bf16 v[62:65], v[134:137], v[180:183], v[62:65]
	s_setprio 1
	v_mfma_f32_16x16x32_bf16 v[50:53], v[134:137], v[210:213], v[50:53]
	v_mfma_f32_16x16x32_bf16 v[50:53], v[130:133], v[184:187], v[50:53]
	v_mfma_f32_16x16x32_bf16 v[34:37], v[130:133], v[214:217], v[34:37]
	v_mfma_f32_16x16x32_bf16 v[34:37], v[134:137], v[218:221], v[34:37]
	v_mfma_f32_16x16x32_bf16 v[18:21], v[134:137], v[226:229], v[18:21]
	v_mfma_f32_16x16x32_bf16 v[18:21], v[130:133], v[222:225], v[18:21]
	v_mfma_f32_16x16x32_bf16 v[10:13], v[138:141], v[222:225], v[10:13]
	v_mfma_f32_16x16x32_bf16 v[10:13], v[142:145], v[226:229], v[10:13]
	v_mfma_f32_16x16x32_bf16 v[26:29], v[142:145], v[218:221], v[26:29]
	v_mfma_f32_16x16x32_bf16 v[26:29], v[138:141], v[214:217], v[26:29]
	v_mfma_f32_16x16x32_bf16 v[42:45], v[138:141], v[184:187], v[42:45]
	v_mfma_f32_16x16x32_bf16 v[42:45], v[142:145], v[210:213], v[42:45]
	v_mfma_f32_16x16x32_bf16 v[58:61], v[142:145], v[180:183], v[58:61]
	v_mfma_f32_16x16x32_bf16 v[58:61], v[138:141], v[176:179], v[58:61]
	v_mfma_f32_16x16x32_bf16 v[46:49], v[168:171], v[176:179], v[46:49]
	v_mfma_f32_16x16x32_bf16 v[46:49], v[172:175], v[180:183], v[46:49]
	v_mfma_f32_16x16x32_bf16 v[30:33], v[172:175], v[210:213], v[30:33]
	v_mfma_f32_16x16x32_bf16 v[30:33], v[168:171], v[184:187], v[30:33]
	v_mfma_f32_16x16x32_bf16 v[14:17], v[168:171], v[214:217], v[14:17]
	v_mfma_f32_16x16x32_bf16 v[14:17], v[172:175], v[218:221], v[14:17]
	v_mfma_f32_16x16x32_bf16 v[2:5], v[172:175], v[226:229], v[2:5]
	v_mfma_f32_16x16x32_bf16 v[2:5], v[168:171], v[222:225], v[2:5]
	v_mfma_f32_16x16x32_bf16 v[6:9], v[156:159], v[222:225], v[6:9]
	v_mfma_f32_16x16x32_bf16 v[6:9], v[164:167], v[226:229], v[6:9]
	v_mfma_f32_16x16x32_bf16 v[22:25], v[164:167], v[218:221], v[22:25]
	v_mfma_f32_16x16x32_bf16 v[22:25], v[156:159], v[214:217], v[22:25]
	v_mfma_f32_16x16x32_bf16 v[38:41], v[156:159], v[184:187], v[38:41]
	v_mfma_f32_16x16x32_bf16 v[38:41], v[164:167], v[210:213], v[38:41]
	v_mfma_f32_16x16x32_bf16 v[54:57], v[164:167], v[180:183], v[54:57]
	s_barrier
	v_mfma_f32_16x16x32_bf16 v[54:57], v[156:159], v[176:179], v[54:57]
	s_setprio 0
	s_add_i32 s74, s74, 2
	s_add_u32 s40, s40, 0x100
	s_addc_u32 s41, s41, 0
	s_add_u32 s73, s73, 0x100
	s_addc_u32 s61, s61, 0
	s_cmp_gt_u32 s74, 13
	s_cbranch_scc0 .LBB0_692
	s_and_b64 vcc, exec, s[30:31]
	s_cbranch_vccz .LBB0_695
	s_barrier

.LBB0_777:
	s_add_u32 s12, s50, 0xfff00080
	s_addc_u32 s13, s51, -1
	s_add_i32 s56, 0, 0x10000
	s_cmp_eq_u32 s72, 60
	s_cselect_b32 s55, s43, s13
	s_cselect_b32 s54, s49, s12
	s_cselect_b32 s53, s41, s61
	s_cselect_b32 s52, s70, s71
	s_add_i32 s73, 0, 0x14000
	v_add_u32_e32 v142, s56, v193
	v_add_u32_e32 v158, s73, v193
	ds_read_b128 v[130:133], v142
	ds_read_b128 v[134:137], v142 offset:1024
	ds_read_b128 v[138:141], v142 offset:2048
	ds_read_b128 v[142:145], v142 offset:3072
	ds_read_b128 v[146:149], v158
	ds_read_b128 v[150:153], v158 offset:1024
	ds_read_b128 v[154:157], v158 offset:2048
	ds_read_b128 v[158:161], v158 offset:3072
	ds_read_b128 v[162:165], v197
	ds_read_b128 v[166:169], v197 offset:1024
	ds_read_b128 v[170:173], v197 offset:2048
	ds_read_b128 v[174:177], v197 offset:3072
	ds_read_b128 v[178:181], v197 offset:4096
	ds_read_b128 v[182:185], v197 offset:5120
	ds_read_b128 v[186:189], v197 offset:6144
	ds_read_b128 v[220:223], v197 offset:7168
	s_add_i32 m0, s33, 0xc000
	s_nop 0
	global_load_lds_dwordx4 v216, s[50:51]
	s_add_i32 m0, s33, 0xe000
	s_nop 0
	global_load_lds_dwordx4 v218, s[50:51]
	s_waitcnt vmcnt(8)
	s_waitcnt lgkmcnt(0)
	s_barrier
	s_waitcnt lgkmcnt(0)
	v_mfma_f32_16x16x32_bf16 v[126:129], v[130:133], v[162:165], v[126:129]
	v_mfma_f32_16x16x32_bf16 v[126:129], v[134:137], v[166:169], v[126:129]
	s_setprio 1
	v_mfma_f32_16x16x32_bf16 v[110:113], v[134:137], v[174:177], v[110:113]
	v_mfma_f32_16x16x32_bf16 v[110:113], v[130:133], v[170:173], v[110:113]
	v_mfma_f32_16x16x32_bf16 v[98:101], v[130:133], v[178:181], v[98:101]
	v_mfma_f32_16x16x32_bf16 v[98:101], v[134:137], v[182:185], v[98:101]
	v_mfma_f32_16x16x32_bf16 v[82:85], v[134:137], v[220:223], v[82:85]
	v_mfma_f32_16x16x32_bf16 v[82:85], v[130:133], v[186:189], v[82:85]
	v_mfma_f32_16x16x32_bf16 v[74:77], v[138:141], v[186:189], v[74:77]
	v_mfma_f32_16x16x32_bf16 v[74:77], v[142:145], v[220:223], v[74:77]
	v_mfma_f32_16x16x32_bf16 v[90:93], v[142:145], v[182:185], v[90:93]
	v_mfma_f32_16x16x32_bf16 v[90:93], v[138:141], v[178:181], v[90:93]
	v_mfma_f32_16x16x32_bf16 v[106:109], v[138:141], v[170:173], v[106:109]
	v_mfma_f32_16x16x32_bf16 v[106:109], v[142:145], v[174:177], v[106:109]
	v_mfma_f32_16x16x32_bf16 v[122:125], v[142:145], v[166:169], v[122:125]
	v_mfma_f32_16x16x32_bf16 v[122:125], v[138:141], v[162:165], v[122:125]
	v_mfma_f32_16x16x32_bf16 v[114:117], v[154:157], v[162:165], v[114:117]
	v_mfma_f32_16x16x32_bf16 v[114:117], v[158:161], v[166:169], v[114:117]
	v_mfma_f32_16x16x32_bf16 v[94:97], v[158:161], v[174:177], v[94:97]
	v_mfma_f32_16x16x32_bf16 v[94:97], v[154:157], v[170:173], v[94:97]
	v_mfma_f32_16x16x32_bf16 v[78:81], v[154:157], v[178:181], v[78:81]
	v_mfma_f32_16x16x32_bf16 v[78:81], v[158:161], v[182:185], v[78:81]
	v_mfma_f32_16x16x32_bf16 v[66:69], v[158:161], v[220:223], v[66:69]
	v_mfma_f32_16x16x32_bf16 v[66:69], v[154:157], v[186:189], v[66:69]
	v_mfma_f32_16x16x32_bf16 v[70:73], v[146:149], v[186:189], v[70:73]
	v_mfma_f32_16x16x32_bf16 v[70:73], v[150:153], v[220:223], v[70:73]
	v_mfma_f32_16x16x32_bf16 v[86:89], v[150:153], v[182:185], v[86:89]
	v_mfma_f32_16x16x32_bf16 v[86:89], v[146:149], v[178:181], v[86:89]
	v_mfma_f32_16x16x32_bf16 v[102:105], v[146:149], v[170:173], v[102:105]
	v_mfma_f32_16x16x32_bf16 v[102:105], v[150:153], v[174:177], v[102:105]
	v_mfma_f32_16x16x32_bf16 v[118:121], v[150:153], v[166:169], v[118:121]
	s_barrier
	v_mfma_f32_16x16x32_bf16 v[118:121], v[146:149], v[162:165], v[118:121]
	s_setprio 0
	s_add_i32 s12, s56, s29
	ds_read_b128 v[162:165], v197 offset:16384
	ds_read_b128 v[166:169], v197 offset:17408
	ds_read_b128 v[170:173], v197 offset:18432
	ds_read_b128 v[174:177], v197 offset:19456
	ds_read_b128 v[178:181], v197 offset:20480
	ds_read_b128 v[182:185], v197 offset:21504
	ds_read_b128 v[186:189], v197 offset:22528
	ds_read_b128 v[220:223], v197 offset:23552
	s_mov_b32 m0, s12
	s_nop 0
	global_load_lds_dwordx4 v190, s[52:53]
	s_add_i32 m0, s12, 0x2000
	s_add_u32 s12, s52, 0x100000
	s_addc_u32 s13, s53, 0
	s_add_i32 s56, s73, s29
	global_load_lds_dwordx4 v214, s[52:53]
	s_mov_b32 m0, s56
	s_nop 0
	global_load_lds_dwordx4 v190, s[12:13]
	s_add_i32 m0, s56, 0x2000
	s_nop 0
	global_load_lds_dwordx4 v214, s[12:13]
	s_mov_b32 m0, s33
	s_nop 0
	global_load_lds_dwordx4 v210, s[54:55]
	s_mov_b32 m0, s62
	s_nop 0
	global_load_lds_dwordx4 v212, s[54:55]
	s_waitcnt vmcnt(8)
	s_waitcnt lgkmcnt(0)
	s_barrier
	s_waitcnt lgkmcnt(0)
	v_mfma_f32_16x16x32_bf16 v[62:65], v[130:133], v[162:165], v[62:65]
	v_mfma_f32_16x16x32_bf16 v[62:65], v[134:137], v[166:169], v[62:65]
	s_setprio 1
	v_mfma_f32_16x16x32_bf16 v[50:53], v[134:137], v[174:177], v[50:53]
	v_mfma_f32_16x16x32_bf16 v[50:53], v[130:133], v[170:173], v[50:53]
	v_mfma_f32_16x16x32_bf16 v[34:37], v[130:133], v[178:181], v[34:37]
	v_mfma_f32_16x16x32_bf16 v[34:37], v[134:137], v[182:185], v[34:37]
	v_mfma_f32_16x16x32_bf16 v[18:21], v[134:137], v[220:223], v[18:21]
	v_mfma_f32_16x16x32_bf16 v[18:21], v[130:133], v[186:189], v[18:21]
	v_mfma_f32_16x16x32_bf16 v[10:13], v[138:141], v[186:189], v[10:13]
	v_mfma_f32_16x16x32_bf16 v[10:13], v[142:145], v[220:223], v[10:13]
	v_mfma_f32_16x16x32_bf16 v[26:29], v[142:145], v[182:185], v[26:29]
	v_mfma_f32_16x16x32_bf16 v[26:29], v[138:141], v[178:181], v[26:29]
	v_mfma_f32_16x16x32_bf16 v[42:45], v[138:141], v[170:173], v[42:45]
	v_mfma_f32_16x16x32_bf16 v[42:45], v[142:145], v[174:177], v[42:45]
	v_mfma_f32_16x16x32_bf16 v[58:61], v[142:145], v[166:169], v[58:61]
	v_mfma_f32_16x16x32_bf16 v[58:61], v[138:141], v[162:165], v[58:61]
	v_mfma_f32_16x16x32_bf16 v[46:49], v[154:157], v[162:165], v[46:49]
	v_mfma_f32_16x16x32_bf16 v[46:49], v[158:161], v[166:169], v[46:49]
	v_mfma_f32_16x16x32_bf16 v[30:33], v[158:161], v[174:177], v[30:33]
	v_mfma_f32_16x16x32_bf16 v[30:33], v[154:157], v[170:173], v[30:33]
	v_mfma_f32_16x16x32_bf16 v[14:17], v[154:157], v[178:181], v[14:17]
	v_mfma_f32_16x16x32_bf16 v[14:17], v[158:161], v[182:185], v[14:17]
	v_mfma_f32_16x16x32_bf16 v[2:5], v[158:161], v[220:223], v[2:5]
	v_mfma_f32_16x16x32_bf16 v[2:5], v[154:157], v[186:189], v[2:5]
	v_mfma_f32_16x16x32_bf16 v[6:9], v[146:149], v[186:189], v[6:9]
	v_mfma_f32_16x16x32_bf16 v[6:9], v[150:153], v[220:223], v[6:9]
	v_mfma_f32_16x16x32_bf16 v[22:25], v[150:153], v[182:185], v[22:25]
	v_mfma_f32_16x16x32_bf16 v[22:25], v[146:149], v[178:181], v[22:25]
	v_mfma_f32_16x16x32_bf16 v[38:41], v[146:149], v[170:173], v[38:41]
	v_mfma_f32_16x16x32_bf16 v[38:41], v[150:153], v[174:177], v[38:41]
	v_mfma_f32_16x16x32_bf16 v[54:57], v[150:153], v[166:169], v[54:57]
	s_barrier
	v_mfma_f32_16x16x32_bf16 v[54:57], v[146:149], v[162:165], v[54:57]
	s_setprio 0
	s_add_i32 s56, 0, 0x18000
	s_add_i32 s73, 0, 0x1c000
	s_add_u32 s12, s54, 0x100000
	s_addc_u32 s13, s55, 0
	v_add_u32_e32 v142, s56, v193
	v_add_u32_e32 v158, s73, v193
	ds_read_b128 v[130:133], v142
	ds_read_b128 v[134:137], v142 offset:1024
	ds_read_b128 v[138:141], v142 offset:2048
	ds_read_b128 v[142:145], v142 offset:3072
	ds_read_b128 v[146:149], v158
	ds_read_b128 v[150:153], v158 offset:1024
	ds_read_b128 v[154:157], v158 offset:2048
	ds_read_b128 v[158:161], v158 offset:3072
	ds_read_b128 v[162:165], v197 offset:32768
	ds_read_b128 v[166:169], v197 offset:33792
	ds_read_b128 v[170:173], v197 offset:34816
	ds_read_b128 v[174:177], v197 offset:35840
	ds_read_b128 v[178:181], v197 offset:36864
	ds_read_b128 v[182:185], v197 offset:37888
	ds_read_b128 v[186:189], v197 offset:38912
	ds_read_b128 v[220:223], v197 offset:39936
	s_mov_b32 m0, s63
	s_nop 0
	global_load_lds_dwordx4 v210, s[12:13]
	s_mov_b32 m0, s64
	s_nop 0
	global_load_lds_dwordx4 v212, s[12:13]
	s_waitcnt vmcnt(8)
	s_waitcnt lgkmcnt(0)
	s_barrier
	s_waitcnt lgkmcnt(0)
	v_mfma_f32_16x16x32_bf16 v[126:129], v[130:133], v[162:165], v[126:129]
	v_mfma_f32_16x16x32_bf16 v[126:129], v[134:137], v[166:169], v[126:129]
	s_setprio 1
	v_mfma_f32_16x16x32_bf16 v[110:113], v[134:137], v[174:177], v[110:113]
	v_mfma_f32_16x16x32_bf16 v[110:113], v[130:133], v[170:173], v[110:113]
	v_mfma_f32_16x16x32_bf16 v[98:101], v[130:133], v[178:181], v[98:101]
	v_mfma_f32_16x16x32_bf16 v[98:101], v[134:137], v[182:185], v[98:101]
	v_mfma_f32_16x16x32_bf16 v[82:85], v[134:137], v[220:223], v[82:85]
	v_mfma_f32_16x16x32_bf16 v[82:85], v[130:133], v[186:189], v[82:85]
	v_mfma_f32_16x16x32_bf16 v[74:77], v[138:141], v[186:189], v[74:77]
	v_mfma_f32_16x16x32_bf16 v[74:77], v[142:145], v[220:223], v[74:77]
	v_mfma_f32_16x16x32_bf16 v[90:93], v[142:145], v[182:185], v[90:93]
	v_mfma_f32_16x16x32_bf16 v[90:93], v[138:141], v[178:181], v[90:93]
	v_mfma_f32_16x16x32_bf16 v[106:109], v[138:141], v[170:173], v[106:109]
	v_mfma_f32_16x16x32_bf16 v[106:109], v[142:145], v[174:177], v[106:109]
	v_mfma_f32_16x16x32_bf16 v[122:125], v[142:145], v[166:169], v[122:125]
	v_mfma_f32_16x16x32_bf16 v[122:125], v[138:141], v[162:165], v[122:125]
	v_mfma_f32_16x16x32_bf16 v[114:117], v[154:157], v[162:165], v[114:117]
	v_mfma_f32_16x16x32_bf16 v[114:117], v[158:161], v[166:169], v[114:117]
	v_mfma_f32_16x16x32_bf16 v[94:97], v[158:161], v[174:177], v[94:97]
	v_mfma_f32_16x16x32_bf16 v[94:97], v[154:157], v[170:173], v[94:97]
	v_mfma_f32_16x16x32_bf16 v[78:81], v[154:157], v[178:181], v[78:81]
	v_mfma_f32_16x16x32_bf16 v[78:81], v[158:161], v[182:185], v[78:81]
	v_mfma_f32_16x16x32_bf16 v[66:69], v[158:161], v[220:223], v[66:69]
	v_mfma_f32_16x16x32_bf16 v[66:69], v[154:157], v[186:189], v[66:69]
	v_mfma_f32_16x16x32_bf16 v[70:73], v[146:149], v[186:189], v[70:73]
	v_mfma_f32_16x16x32_bf16 v[70:73], v[150:153], v[220:223], v[70:73]
	v_mfma_f32_16x16x32_bf16 v[86:89], v[150:153], v[182:185], v[86:89]
	v_mfma_f32_16x16x32_bf16 v[86:89], v[146:149], v[178:181], v[86:89]
	v_mfma_f32_16x16x32_bf16 v[102:105], v[146:149], v[170:173], v[102:105]
	v_mfma_f32_16x16x32_bf16 v[102:105], v[150:153], v[174:177], v[102:105]
	v_mfma_f32_16x16x32_bf16 v[118:121], v[150:153], v[166:169], v[118:121]
	s_barrier
	v_mfma_f32_16x16x32_bf16 v[118:121], v[146:149], v[162:165], v[118:121]
	s_setprio 0
	s_add_i32 s12, s56, s29
	ds_read_b128 v[162:165], v197 offset:49152
	ds_read_b128 v[166:169], v197 offset:50176
	ds_read_b128 v[170:173], v197 offset:51200
	ds_read_b128 v[174:177], v197 offset:52224
	ds_read_b128 v[178:181], v197 offset:53248
	ds_read_b128 v[182:185], v197 offset:54272
	ds_read_b128 v[186:189], v197 offset:55296
	ds_read_b128 v[220:223], v197 offset:56320
	s_mov_b32 m0, s12
	s_nop 0
	global_load_lds_dwordx4 v224, s[52:53]
	s_add_i32 m0, s12, 0x2000
	s_add_u32 s12, s52, 0x100080
	s_addc_u32 s13, s53, 0
	global_load_lds_dwordx4 v227, s[52:53]
	s_add_i32 s52, s73, s29
	s_mov_b32 m0, s52
	s_nop 0
	global_load_lds_dwordx4 v190, s[12:13]
	s_add_i32 m0, s52, 0x2000
	s_nop 0
	global_load_lds_dwordx4 v214, s[12:13]
	s_mov_b32 m0, s65
	s_nop 0
	global_load_lds_dwordx4 v225, s[54:55]
	s_mov_b32 m0, s66
	s_nop 0
	global_load_lds_dwordx4 v226, s[54:55]
	s_waitcnt vmcnt(8)
	s_waitcnt lgkmcnt(0)
	s_barrier
	s_waitcnt lgkmcnt(0)
	v_mfma_f32_16x16x32_bf16 v[62:65], v[130:133], v[162:165], v[62:65]
	v_mfma_f32_16x16x32_bf16 v[62:65], v[134:137], v[166:169], v[62:65]
	s_setprio 1
	v_mfma_f32_16x16x32_bf16 v[50:53], v[134:137], v[174:177], v[50:53]
	v_mfma_f32_16x16x32_bf16 v[50:53], v[130:133], v[170:173], v[50:53]
	v_mfma_f32_16x16x32_bf16 v[34:37], v[130:133], v[178:181], v[34:37]
	v_mfma_f32_16x16x32_bf16 v[34:37], v[134:137], v[182:185], v[34:37]
	v_mfma_f32_16x16x32_bf16 v[18:21], v[134:137], v[220:223], v[18:21]
	v_mfma_f32_16x16x32_bf16 v[18:21], v[130:133], v[186:189], v[18:21]
	v_mfma_f32_16x16x32_bf16 v[10:13], v[138:141], v[186:189], v[10:13]
	v_mfma_f32_16x16x32_bf16 v[10:13], v[142:145], v[220:223], v[10:13]
	v_mfma_f32_16x16x32_bf16 v[26:29], v[142:145], v[182:185], v[26:29]
	v_mfma_f32_16x16x32_bf16 v[26:29], v[138:141], v[178:181], v[26:29]
	v_mfma_f32_16x16x32_bf16 v[42:45], v[138:141], v[170:173], v[42:45]
	v_mfma_f32_16x16x32_bf16 v[42:45], v[142:145], v[174:177], v[42:45]
	v_mfma_f32_16x16x32_bf16 v[58:61], v[142:145], v[166:169], v[58:61]
	v_mfma_f32_16x16x32_bf16 v[58:61], v[138:141], v[162:165], v[58:61]
	v_mfma_f32_16x16x32_bf16 v[46:49], v[154:157], v[162:165], v[46:49]
	v_mfma_f32_16x16x32_bf16 v[46:49], v[158:161], v[166:169], v[46:49]
	v_mfma_f32_16x16x32_bf16 v[30:33], v[158:161], v[174:177], v[30:33]
	v_mfma_f32_16x16x32_bf16 v[30:33], v[154:157], v[170:173], v[30:33]
	v_mfma_f32_16x16x32_bf16 v[14:17], v[154:157], v[178:181], v[14:17]
	v_mfma_f32_16x16x32_bf16 v[14:17], v[158:161], v[182:185], v[14:17]
	v_mfma_f32_16x16x32_bf16 v[2:5], v[158:161], v[220:223], v[2:5]
	v_mfma_f32_16x16x32_bf16 v[2:5], v[154:157], v[186:189], v[2:5]
	v_mfma_f32_16x16x32_bf16 v[6:9], v[146:149], v[186:189], v[6:9]
	v_mfma_f32_16x16x32_bf16 v[6:9], v[150:153], v[220:223], v[6:9]
	v_mfma_f32_16x16x32_bf16 v[22:25], v[150:153], v[182:185], v[22:25]
	v_mfma_f32_16x16x32_bf16 v[22:25], v[146:149], v[178:181], v[22:25]
	v_mfma_f32_16x16x32_bf16 v[38:41], v[146:149], v[170:173], v[38:41]
	v_mfma_f32_16x16x32_bf16 v[38:41], v[150:153], v[174:177], v[38:41]
	v_mfma_f32_16x16x32_bf16 v[54:57], v[150:153], v[166:169], v[54:57]
	s_barrier
	v_mfma_f32_16x16x32_bf16 v[54:57], v[146:149], v[162:165], v[54:57]
	s_setprio 0
	s_add_i32 s72, s72, 2
	s_add_u32 s50, s50, 0x100
	s_addc_u32 s51, s51, 0
	s_add_u32 s71, s71, 0x100
	s_addc_u32 s61, s61, 0
	s_cmp_gt_u32 s72, 61
	s_cbranch_scc0 .LBB0_777
	s_and_b64 vcc, exec, s[30:31]
	s_cbranch_vccz .LBB0_780
	s_barrier

.LBB0_902:
	s_add_u32 s12, s22, 0xfff00080
	s_addc_u32 s13, s23, -1
	s_add_i32 s56, 0, 0x10000
	s_cmp_eq_u32 s47, 60
	s_cselect_b32 s53, s5, s13
	s_cselect_b32 s52, s10, s12
	s_cselect_b32 s31, s25, s45
	s_cselect_b32 s30, s29, s33
	s_add_i32 s61, 0, 0x14000
	v_add_u32_e32 v147, s56, v144
	ds_read_b128 v[140:143], v147
	ds_read_b128 v[148:151], v147 offset:1024
	ds_read_b128 v[152:155], v147 offset:2048
	ds_read_b128 v[156:159], v147 offset:3072
	v_add_u32_e32 v147, s61, v144
	ds_read_b128 v[160:163], v147
	ds_read_b128 v[164:167], v147 offset:1024
	ds_read_b128 v[168:171], v147 offset:2048
	ds_read_b128 v[172:175], v147 offset:3072
	ds_read_b128 v[176:179], v146
	ds_read_b128 v[180:183], v146 offset:1024
	ds_read_b128 v[184:187], v146 offset:2048
	ds_read_b128 v[210:213], v146 offset:3072
	ds_read_b128 v[214:217], v146 offset:4096
	ds_read_b128 v[218:221], v146 offset:5120
	ds_read_b128 v[222:225], v146 offset:6144
	ds_read_b128 v[226:229], v146 offset:7168
	s_add_i32 m0, s63, 0xc000
	s_nop 0
	global_load_lds_dwordx4 v136, s[22:23]
	s_add_i32 m0, s63, 0xe000
	s_nop 0
	global_load_lds_dwordx4 v138, s[22:23]
	s_waitcnt vmcnt(8)
	s_waitcnt lgkmcnt(0)
	s_barrier
	s_waitcnt lgkmcnt(0)
	v_mfma_f32_16x16x32_bf16 v[126:129], v[140:143], v[176:179], v[126:129]
	v_mfma_f32_16x16x32_bf16 v[126:129], v[148:151], v[180:183], v[126:129]
	s_setprio 1
	v_mfma_f32_16x16x32_bf16 v[110:113], v[148:151], v[210:213], v[110:113]
	v_mfma_f32_16x16x32_bf16 v[110:113], v[140:143], v[184:187], v[110:113]
	v_mfma_f32_16x16x32_bf16 v[94:97], v[140:143], v[214:217], v[94:97]
	v_mfma_f32_16x16x32_bf16 v[94:97], v[148:151], v[218:221], v[94:97]
	v_mfma_f32_16x16x32_bf16 v[78:81], v[148:151], v[226:229], v[78:81]
	v_mfma_f32_16x16x32_bf16 v[78:81], v[140:143], v[222:225], v[78:81]
	v_mfma_f32_16x16x32_bf16 v[70:73], v[152:155], v[222:225], v[70:73]
	v_mfma_f32_16x16x32_bf16 v[70:73], v[156:159], v[226:229], v[70:73]
	v_mfma_f32_16x16x32_bf16 v[86:89], v[156:159], v[218:221], v[86:89]
	v_mfma_f32_16x16x32_bf16 v[86:89], v[152:155], v[214:217], v[86:89]
	v_mfma_f32_16x16x32_bf16 v[102:105], v[152:155], v[184:187], v[102:105]
	v_mfma_f32_16x16x32_bf16 v[102:105], v[156:159], v[210:213], v[102:105]
	v_mfma_f32_16x16x32_bf16 v[118:121], v[156:159], v[180:183], v[118:121]
	v_mfma_f32_16x16x32_bf16 v[118:121], v[152:155], v[176:179], v[118:121]
	v_mfma_f32_16x16x32_bf16 v[114:117], v[168:171], v[176:179], v[114:117]
	v_mfma_f32_16x16x32_bf16 v[114:117], v[172:175], v[180:183], v[114:117]
	v_mfma_f32_16x16x32_bf16 v[98:101], v[172:175], v[210:213], v[98:101]
	v_mfma_f32_16x16x32_bf16 v[98:101], v[168:171], v[184:187], v[98:101]
	v_mfma_f32_16x16x32_bf16 v[82:85], v[168:171], v[214:217], v[82:85]
	v_mfma_f32_16x16x32_bf16 v[82:85], v[172:175], v[218:221], v[82:85]
	v_mfma_f32_16x16x32_bf16 v[66:69], v[172:175], v[226:229], v[66:69]
	v_mfma_f32_16x16x32_bf16 v[66:69], v[168:171], v[222:225], v[66:69]
	v_mfma_f32_16x16x32_bf16 v[74:77], v[160:163], v[222:225], v[74:77]
	v_mfma_f32_16x16x32_bf16 v[74:77], v[164:167], v[226:229], v[74:77]
	v_mfma_f32_16x16x32_bf16 v[90:93], v[164:167], v[218:221], v[90:93]
	v_mfma_f32_16x16x32_bf16 v[90:93], v[160:163], v[214:217], v[90:93]
	v_mfma_f32_16x16x32_bf16 v[106:109], v[160:163], v[184:187], v[106:109]
	v_mfma_f32_16x16x32_bf16 v[106:109], v[164:167], v[210:213], v[106:109]
	v_mfma_f32_16x16x32_bf16 v[122:125], v[164:167], v[180:183], v[122:125]
	s_barrier
	v_mfma_f32_16x16x32_bf16 v[122:125], v[160:163], v[176:179], v[122:125]
	s_setprio 0
	s_add_i32 s12, s56, s60
	ds_read_b128 v[176:179], v146 offset:16384
	ds_read_b128 v[180:183], v146 offset:17408
	ds_read_b128 v[184:187], v146 offset:18432
	ds_read_b128 v[210:213], v146 offset:19456
	ds_read_b128 v[214:217], v146 offset:20480
	ds_read_b128 v[218:221], v146 offset:21504
	ds_read_b128 v[222:225], v146 offset:22528
	ds_read_b128 v[226:229], v146 offset:23552
	s_mov_b32 m0, s12
	s_nop 0
	global_load_lds_dwordx4 v190, s[30:31]
	s_add_i32 m0, s12, 0x2000
	s_add_u32 s12, s30, 0x100000
	s_addc_u32 s13, s31, 0
	s_add_i32 s56, s61, s60
	global_load_lds_dwordx4 v130, s[30:31]
	s_mov_b32 m0, s56
	s_nop 0
	global_load_lds_dwordx4 v190, s[12:13]
	s_add_i32 m0, s56, 0x2000
	s_nop 0
	global_load_lds_dwordx4 v130, s[12:13]
	s_mov_b32 m0, s63
	s_nop 0
	global_load_lds_dwordx4 v134, s[52:53]
	s_mov_b32 m0, s64
	s_nop 0
	global_load_lds_dwordx4 v132, s[52:53]
	s_waitcnt vmcnt(8)
	s_waitcnt lgkmcnt(0)
	s_barrier
	s_waitcnt lgkmcnt(0)
	v_mfma_f32_16x16x32_bf16 v[62:65], v[140:143], v[176:179], v[62:65]
	v_mfma_f32_16x16x32_bf16 v[62:65], v[148:151], v[180:183], v[62:65]
	s_setprio 1
	v_mfma_f32_16x16x32_bf16 v[46:49], v[148:151], v[210:213], v[46:49]
	v_mfma_f32_16x16x32_bf16 v[46:49], v[140:143], v[184:187], v[46:49]
	v_mfma_f32_16x16x32_bf16 v[30:33], v[140:143], v[214:217], v[30:33]
	v_mfma_f32_16x16x32_bf16 v[30:33], v[148:151], v[218:221], v[30:33]
	v_mfma_f32_16x16x32_bf16 v[14:17], v[148:151], v[226:229], v[14:17]
	v_mfma_f32_16x16x32_bf16 v[14:17], v[140:143], v[222:225], v[14:17]
	v_mfma_f32_16x16x32_bf16 v[6:9], v[152:155], v[222:225], v[6:9]
	v_mfma_f32_16x16x32_bf16 v[6:9], v[156:159], v[226:229], v[6:9]
	v_mfma_f32_16x16x32_bf16 v[22:25], v[156:159], v[218:221], v[22:25]
	v_mfma_f32_16x16x32_bf16 v[22:25], v[152:155], v[214:217], v[22:25]
	v_mfma_f32_16x16x32_bf16 v[38:41], v[152:155], v[184:187], v[38:41]
	v_mfma_f32_16x16x32_bf16 v[38:41], v[156:159], v[210:213], v[38:41]
	v_mfma_f32_16x16x32_bf16 v[54:57], v[156:159], v[180:183], v[54:57]
	v_mfma_f32_16x16x32_bf16 v[54:57], v[152:155], v[176:179], v[54:57]
	v_mfma_f32_16x16x32_bf16 v[50:53], v[168:171], v[176:179], v[50:53]
	v_mfma_f32_16x16x32_bf16 v[50:53], v[172:175], v[180:183], v[50:53]
	v_mfma_f32_16x16x32_bf16 v[34:37], v[172:175], v[210:213], v[34:37]
	v_mfma_f32_16x16x32_bf16 v[34:37], v[168:171], v[184:187], v[34:37]
	v_mfma_f32_16x16x32_bf16 v[18:21], v[168:171], v[214:217], v[18:21]
	v_mfma_f32_16x16x32_bf16 v[18:21], v[172:175], v[218:221], v[18:21]
	v_mfma_f32_16x16x32_bf16 v[2:5], v[172:175], v[226:229], v[2:5]
	v_mfma_f32_16x16x32_bf16 v[2:5], v[168:171], v[222:225], v[2:5]
	v_mfma_f32_16x16x32_bf16 v[10:13], v[160:163], v[222:225], v[10:13]
	v_mfma_f32_16x16x32_bf16 v[10:13], v[164:167], v[226:229], v[10:13]
	v_mfma_f32_16x16x32_bf16 v[26:29], v[164:167], v[218:221], v[26:29]
	v_mfma_f32_16x16x32_bf16 v[26:29], v[160:163], v[214:217], v[26:29]
	v_mfma_f32_16x16x32_bf16 v[42:45], v[160:163], v[184:187], v[42:45]
	v_mfma_f32_16x16x32_bf16 v[42:45], v[164:167], v[210:213], v[42:45]
	v_mfma_f32_16x16x32_bf16 v[58:61], v[164:167], v[180:183], v[58:61]
	s_barrier
	v_mfma_f32_16x16x32_bf16 v[58:61], v[160:163], v[176:179], v[58:61]
	s_setprio 0
	s_add_i32 s56, 0, 0x18000
	s_add_i32 s61, 0, 0x1c000
	s_add_u32 s12, s52, 0x100000
	s_addc_u32 s13, s53, 0
	v_add_u32_e32 v147, s56, v144
	ds_read_b128 v[140:143], v147
	ds_read_b128 v[148:151], v147 offset:1024
	ds_read_b128 v[152:155], v147 offset:2048
	ds_read_b128 v[156:159], v147 offset:3072
	v_add_u32_e32 v147, s61, v144
	ds_read_b128 v[160:163], v147
	ds_read_b128 v[164:167], v147 offset:1024
	ds_read_b128 v[168:171], v147 offset:2048
	ds_read_b128 v[172:175], v147 offset:3072
	ds_read_b128 v[176:179], v146 offset:32768
	ds_read_b128 v[180:183], v146 offset:33792
	ds_read_b128 v[184:187], v146 offset:34816
	ds_read_b128 v[210:213], v146 offset:35840
	ds_read_b128 v[214:217], v146 offset:36864
	ds_read_b128 v[218:221], v146 offset:37888
	ds_read_b128 v[222:225], v146 offset:38912
	ds_read_b128 v[226:229], v146 offset:39936
	s_mov_b32 m0, s65
	s_nop 0
	global_load_lds_dwordx4 v134, s[12:13]
	s_mov_b32 m0, s66
	s_nop 0
	global_load_lds_dwordx4 v132, s[12:13]
	s_waitcnt vmcnt(8)
	s_waitcnt lgkmcnt(0)
	s_barrier
	s_waitcnt lgkmcnt(0)
	v_mfma_f32_16x16x32_bf16 v[126:129], v[140:143], v[176:179], v[126:129]
	v_mfma_f32_16x16x32_bf16 v[126:129], v[148:151], v[180:183], v[126:129]
	s_setprio 1
	v_mfma_f32_16x16x32_bf16 v[110:113], v[148:151], v[210:213], v[110:113]
	v_mfma_f32_16x16x32_bf16 v[110:113], v[140:143], v[184:187], v[110:113]
	v_mfma_f32_16x16x32_bf16 v[94:97], v[140:143], v[214:217], v[94:97]
	v_mfma_f32_16x16x32_bf16 v[94:97], v[148:151], v[218:221], v[94:97]
	v_mfma_f32_16x16x32_bf16 v[78:81], v[148:151], v[226:229], v[78:81]
	v_mfma_f32_16x16x32_bf16 v[78:81], v[140:143], v[222:225], v[78:81]
	v_mfma_f32_16x16x32_bf16 v[70:73], v[152:155], v[222:225], v[70:73]
	v_mfma_f32_16x16x32_bf16 v[70:73], v[156:159], v[226:229], v[70:73]
	v_mfma_f32_16x16x32_bf16 v[86:89], v[156:159], v[218:221], v[86:89]
	v_mfma_f32_16x16x32_bf16 v[86:89], v[152:155], v[214:217], v[86:89]
	v_mfma_f32_16x16x32_bf16 v[102:105], v[152:155], v[184:187], v[102:105]
	v_mfma_f32_16x16x32_bf16 v[102:105], v[156:159], v[210:213], v[102:105]
	v_mfma_f32_16x16x32_bf16 v[118:121], v[156:159], v[180:183], v[118:121]
	v_mfma_f32_16x16x32_bf16 v[118:121], v[152:155], v[176:179], v[118:121]
	v_mfma_f32_16x16x32_bf16 v[114:117], v[168:171], v[176:179], v[114:117]
	v_mfma_f32_16x16x32_bf16 v[114:117], v[172:175], v[180:183], v[114:117]
	v_mfma_f32_16x16x32_bf16 v[98:101], v[172:175], v[210:213], v[98:101]
	v_mfma_f32_16x16x32_bf16 v[98:101], v[168:171], v[184:187], v[98:101]
	v_mfma_f32_16x16x32_bf16 v[82:85], v[168:171], v[214:217], v[82:85]
	v_mfma_f32_16x16x32_bf16 v[82:85], v[172:175], v[218:221], v[82:85]
	v_mfma_f32_16x16x32_bf16 v[66:69], v[172:175], v[226:229], v[66:69]
	v_mfma_f32_16x16x32_bf16 v[66:69], v[168:171], v[222:225], v[66:69]
	v_mfma_f32_16x16x32_bf16 v[74:77], v[160:163], v[222:225], v[74:77]
	v_mfma_f32_16x16x32_bf16 v[74:77], v[164:167], v[226:229], v[74:77]
	v_mfma_f32_16x16x32_bf16 v[90:93], v[164:167], v[218:221], v[90:93]
	v_mfma_f32_16x16x32_bf16 v[90:93], v[160:163], v[214:217], v[90:93]
	v_mfma_f32_16x16x32_bf16 v[106:109], v[160:163], v[184:187], v[106:109]
	v_mfma_f32_16x16x32_bf16 v[106:109], v[164:167], v[210:213], v[106:109]
	v_mfma_f32_16x16x32_bf16 v[122:125], v[164:167], v[180:183], v[122:125]
	s_barrier
	v_mfma_f32_16x16x32_bf16 v[122:125], v[160:163], v[176:179], v[122:125]
	s_setprio 0
	s_add_i32 s12, s56, s60
	ds_read_b128 v[176:179], v146 offset:49152
	ds_read_b128 v[180:183], v146 offset:50176
	ds_read_b128 v[184:187], v146 offset:51200
	ds_read_b128 v[210:213], v146 offset:52224
	ds_read_b128 v[214:217], v146 offset:53248
	ds_read_b128 v[218:221], v146 offset:54272
	ds_read_b128 v[222:225], v146 offset:55296
	ds_read_b128 v[226:229], v146 offset:56320
	s_mov_b32 m0, s12
	s_nop 0
	global_load_lds_dwordx4 v231, s[30:31]
	s_add_i32 m0, s12, 0x2000
	s_add_u32 s12, s30, 0x100080
	s_addc_u32 s13, s31, 0
	global_load_lds_dwordx4 v188, s[30:31]
	s_add_i32 s30, s61, s60
	s_mov_b32 m0, s30
	s_nop 0
	global_load_lds_dwordx4 v190, s[12:13]
	s_add_i32 m0, s30, 0x2000
	s_nop 0
	global_load_lds_dwordx4 v130, s[12:13]
	s_mov_b32 m0, s68
	s_nop 0
	global_load_lds_dwordx4 v230, s[52:53]
	s_mov_b32 m0, s69
	s_nop 0
	global_load_lds_dwordx4 v189, s[52:53]
	s_waitcnt vmcnt(8)
	s_waitcnt lgkmcnt(0)
	s_barrier
	s_waitcnt lgkmcnt(0)
	v_mfma_f32_16x16x32_bf16 v[62:65], v[140:143], v[176:179], v[62:65]
	v_mfma_f32_16x16x32_bf16 v[62:65], v[148:151], v[180:183], v[62:65]
	s_setprio 1
	v_mfma_f32_16x16x32_bf16 v[46:49], v[148:151], v[210:213], v[46:49]
	v_mfma_f32_16x16x32_bf16 v[46:49], v[140:143], v[184:187], v[46:49]
	v_mfma_f32_16x16x32_bf16 v[30:33], v[140:143], v[214:217], v[30:33]
	v_mfma_f32_16x16x32_bf16 v[30:33], v[148:151], v[218:221], v[30:33]
	v_mfma_f32_16x16x32_bf16 v[14:17], v[148:151], v[226:229], v[14:17]
	v_mfma_f32_16x16x32_bf16 v[14:17], v[140:143], v[222:225], v[14:17]
	v_mfma_f32_16x16x32_bf16 v[6:9], v[152:155], v[222:225], v[6:9]
	v_mfma_f32_16x16x32_bf16 v[6:9], v[156:159], v[226:229], v[6:9]
	v_mfma_f32_16x16x32_bf16 v[22:25], v[156:159], v[218:221], v[22:25]
	v_mfma_f32_16x16x32_bf16 v[22:25], v[152:155], v[214:217], v[22:25]
	v_mfma_f32_16x16x32_bf16 v[38:41], v[152:155], v[184:187], v[38:41]
	v_mfma_f32_16x16x32_bf16 v[38:41], v[156:159], v[210:213], v[38:41]
	v_mfma_f32_16x16x32_bf16 v[54:57], v[156:159], v[180:183], v[54:57]
	v_mfma_f32_16x16x32_bf16 v[54:57], v[152:155], v[176:179], v[54:57]
	v_mfma_f32_16x16x32_bf16 v[50:53], v[168:171], v[176:179], v[50:53]
	v_mfma_f32_16x16x32_bf16 v[50:53], v[172:175], v[180:183], v[50:53]
	v_mfma_f32_16x16x32_bf16 v[34:37], v[172:175], v[210:213], v[34:37]
	v_mfma_f32_16x16x32_bf16 v[34:37], v[168:171], v[184:187], v[34:37]
	v_mfma_f32_16x16x32_bf16 v[18:21], v[168:171], v[214:217], v[18:21]
	v_mfma_f32_16x16x32_bf16 v[18:21], v[172:175], v[218:221], v[18:21]
	v_mfma_f32_16x16x32_bf16 v[2:5], v[172:175], v[226:229], v[2:5]
	v_mfma_f32_16x16x32_bf16 v[2:5], v[168:171], v[222:225], v[2:5]
	v_mfma_f32_16x16x32_bf16 v[10:13], v[160:163], v[222:225], v[10:13]
	v_mfma_f32_16x16x32_bf16 v[10:13], v[164:167], v[226:229], v[10:13]
	v_mfma_f32_16x16x32_bf16 v[26:29], v[164:167], v[218:221], v[26:29]
	v_mfma_f32_16x16x32_bf16 v[26:29], v[160:163], v[214:217], v[26:29]
	v_mfma_f32_16x16x32_bf16 v[42:45], v[160:163], v[184:187], v[42:45]
	v_mfma_f32_16x16x32_bf16 v[42:45], v[164:167], v[210:213], v[42:45]
	v_mfma_f32_16x16x32_bf16 v[58:61], v[164:167], v[180:183], v[58:61]
	s_barrier
	v_mfma_f32_16x16x32_bf16 v[58:61], v[160:163], v[176:179], v[58:61]
	s_setprio 0
	s_add_i32 s47, s47, 2
	s_add_u32 s22, s22, 0x100
	s_addc_u32 s23, s23, 0
	s_add_u32 s33, s33, 0x100
	s_addc_u32 s45, s45, 0
	s_cmp_gt_u32 s47, 61
	s_cbranch_scc0 .LBB0_902
	s_and_b64 vcc, exec, s[42:43]
	s_cbranch_vccz .LBB0_905
	s_barrier

.LBB0_983:
	s_add_u32 s46, s44, 0x100
	s_addc_u32 s47, s45, 0
	s_add_i32 s12, 0, 0x10000
	s_cmpk_eq_i32 s70, 0xa8
	s_cselect_b32 s51, s41, s47
	s_cselect_b32 s50, s40, s46
	s_cselect_b32 s49, s43, s69
	s_cselect_b32 s48, s42, s61
	s_add_i32 s56, 0, 0x14000
	v_add_u32_e32 v142, s12, v193
	v_add_u32_e32 v158, s56, v193
	ds_read_b128 v[130:133], v142
	ds_read_b128 v[134:137], v142 offset:1024
	ds_read_b128 v[138:141], v142 offset:2048
	ds_read_b128 v[142:145], v142 offset:3072
	ds_read_b128 v[146:149], v158
	ds_read_b128 v[150:153], v158 offset:1024
	ds_read_b128 v[154:157], v158 offset:2048
	ds_read_b128 v[158:161], v158 offset:3072
	ds_read_b128 v[162:165], v197
	ds_read_b128 v[166:169], v197 offset:1024
	ds_read_b128 v[170:173], v197 offset:2048
	ds_read_b128 v[174:177], v197 offset:3072
	ds_read_b128 v[178:181], v197 offset:4096
	ds_read_b128 v[182:185], v197 offset:5120
	ds_read_b128 v[186:189], v197 offset:6144
	ds_read_b128 v[220:223], v197 offset:7168
	s_add_i32 m0, s33, 0xc000
	s_nop 0
	global_load_lds_dwordx4 v216, s[44:45]
	s_add_i32 m0, s33, 0xe000
	s_nop 0
	global_load_lds_dwordx4 v218, s[44:45]
	s_waitcnt vmcnt(8)
	s_waitcnt lgkmcnt(0)
	s_barrier
	s_waitcnt lgkmcnt(0)
	v_mfma_f32_16x16x32_bf16 v[126:129], v[130:133], v[162:165], v[126:129]
	v_mfma_f32_16x16x32_bf16 v[126:129], v[134:137], v[166:169], v[126:129]
	s_setprio 1
	v_mfma_f32_16x16x32_bf16 v[110:113], v[134:137], v[174:177], v[110:113]
	v_mfma_f32_16x16x32_bf16 v[110:113], v[130:133], v[170:173], v[110:113]
	v_mfma_f32_16x16x32_bf16 v[98:101], v[130:133], v[178:181], v[98:101]
	v_mfma_f32_16x16x32_bf16 v[98:101], v[134:137], v[182:185], v[98:101]
	v_mfma_f32_16x16x32_bf16 v[82:85], v[134:137], v[220:223], v[82:85]
	v_mfma_f32_16x16x32_bf16 v[82:85], v[130:133], v[186:189], v[82:85]
	v_mfma_f32_16x16x32_bf16 v[74:77], v[138:141], v[186:189], v[74:77]
	v_mfma_f32_16x16x32_bf16 v[74:77], v[142:145], v[220:223], v[74:77]
	v_mfma_f32_16x16x32_bf16 v[90:93], v[142:145], v[182:185], v[90:93]
	v_mfma_f32_16x16x32_bf16 v[90:93], v[138:141], v[178:181], v[90:93]
	v_mfma_f32_16x16x32_bf16 v[106:109], v[138:141], v[170:173], v[106:109]
	v_mfma_f32_16x16x32_bf16 v[106:109], v[142:145], v[174:177], v[106:109]
	v_mfma_f32_16x16x32_bf16 v[122:125], v[142:145], v[166:169], v[122:125]
	v_mfma_f32_16x16x32_bf16 v[122:125], v[138:141], v[162:165], v[122:125]
	v_mfma_f32_16x16x32_bf16 v[114:117], v[154:157], v[162:165], v[114:117]
	v_mfma_f32_16x16x32_bf16 v[114:117], v[158:161], v[166:169], v[114:117]
	v_mfma_f32_16x16x32_bf16 v[94:97], v[158:161], v[174:177], v[94:97]
	v_mfma_f32_16x16x32_bf16 v[94:97], v[154:157], v[170:173], v[94:97]
	v_mfma_f32_16x16x32_bf16 v[78:81], v[154:157], v[178:181], v[78:81]
	v_mfma_f32_16x16x32_bf16 v[78:81], v[158:161], v[182:185], v[78:81]
	v_mfma_f32_16x16x32_bf16 v[66:69], v[158:161], v[220:223], v[66:69]
	v_mfma_f32_16x16x32_bf16 v[66:69], v[154:157], v[186:189], v[66:69]
	v_mfma_f32_16x16x32_bf16 v[70:73], v[146:149], v[186:189], v[70:73]
	v_mfma_f32_16x16x32_bf16 v[70:73], v[150:153], v[220:223], v[70:73]
	v_mfma_f32_16x16x32_bf16 v[86:89], v[150:153], v[182:185], v[86:89]
	v_mfma_f32_16x16x32_bf16 v[86:89], v[146:149], v[178:181], v[86:89]
	v_mfma_f32_16x16x32_bf16 v[102:105], v[146:149], v[170:173], v[102:105]
	v_mfma_f32_16x16x32_bf16 v[102:105], v[150:153], v[174:177], v[102:105]
	v_mfma_f32_16x16x32_bf16 v[118:121], v[150:153], v[166:169], v[118:121]
	s_barrier
	v_mfma_f32_16x16x32_bf16 v[118:121], v[146:149], v[162:165], v[118:121]
	s_setprio 0
	s_add_i32 s12, s12, s29
	ds_read_b128 v[162:165], v197 offset:16384
	ds_read_b128 v[166:169], v197 offset:17408
	ds_read_b128 v[170:173], v197 offset:18432
	ds_read_b128 v[174:177], v197 offset:19456
	ds_read_b128 v[178:181], v197 offset:20480
	ds_read_b128 v[182:185], v197 offset:21504
	ds_read_b128 v[186:189], v197 offset:22528
	ds_read_b128 v[220:223], v197 offset:23552
	s_mov_b32 m0, s12
	s_nop 0
	global_load_lds_dwordx4 v190, s[48:49]
	s_add_i32 m0, s12, 0x2000
	s_add_u32 s12, s48, 0x2b0000
	s_addc_u32 s13, s49, 0
	s_add_i32 s44, s56, s29
	global_load_lds_dwordx4 v214, s[48:49]
	s_mov_b32 m0, s44
	s_nop 0
	global_load_lds_dwordx4 v190, s[12:13]
	s_add_i32 m0, s44, 0x2000
	s_nop 0
	global_load_lds_dwordx4 v214, s[12:13]
	s_mov_b32 m0, s33
	s_nop 0
	global_load_lds_dwordx4 v210, s[50:51]
	s_mov_b32 m0, s57
	s_nop 0
	global_load_lds_dwordx4 v212, s[50:51]
	s_waitcnt vmcnt(8)
	s_waitcnt lgkmcnt(0)
	s_barrier
	s_waitcnt lgkmcnt(0)
	v_mfma_f32_16x16x32_bf16 v[62:65], v[130:133], v[162:165], v[62:65]
	v_mfma_f32_16x16x32_bf16 v[62:65], v[134:137], v[166:169], v[62:65]
	s_setprio 1
	v_mfma_f32_16x16x32_bf16 v[50:53], v[134:137], v[174:177], v[50:53]
	v_mfma_f32_16x16x32_bf16 v[50:53], v[130:133], v[170:173], v[50:53]
	v_mfma_f32_16x16x32_bf16 v[34:37], v[130:133], v[178:181], v[34:37]
	v_mfma_f32_16x16x32_bf16 v[34:37], v[134:137], v[182:185], v[34:37]
	v_mfma_f32_16x16x32_bf16 v[18:21], v[134:137], v[220:223], v[18:21]
	v_mfma_f32_16x16x32_bf16 v[18:21], v[130:133], v[186:189], v[18:21]
	v_mfma_f32_16x16x32_bf16 v[10:13], v[138:141], v[186:189], v[10:13]
	v_mfma_f32_16x16x32_bf16 v[10:13], v[142:145], v[220:223], v[10:13]
	v_mfma_f32_16x16x32_bf16 v[26:29], v[142:145], v[182:185], v[26:29]
	v_mfma_f32_16x16x32_bf16 v[26:29], v[138:141], v[178:181], v[26:29]
	v_mfma_f32_16x16x32_bf16 v[42:45], v[138:141], v[170:173], v[42:45]
	v_mfma_f32_16x16x32_bf16 v[42:45], v[142:145], v[174:177], v[42:45]
	v_mfma_f32_16x16x32_bf16 v[58:61], v[142:145], v[166:169], v[58:61]
	v_mfma_f32_16x16x32_bf16 v[58:61], v[138:141], v[162:165], v[58:61]
	v_mfma_f32_16x16x32_bf16 v[46:49], v[154:157], v[162:165], v[46:49]
	v_mfma_f32_16x16x32_bf16 v[46:49], v[158:161], v[166:169], v[46:49]
	v_mfma_f32_16x16x32_bf16 v[30:33], v[158:161], v[174:177], v[30:33]
	v_mfma_f32_16x16x32_bf16 v[30:33], v[154:157], v[170:173], v[30:33]
	v_mfma_f32_16x16x32_bf16 v[14:17], v[154:157], v[178:181], v[14:17]
	v_mfma_f32_16x16x32_bf16 v[14:17], v[158:161], v[182:185], v[14:17]
	v_mfma_f32_16x16x32_bf16 v[2:5], v[158:161], v[220:223], v[2:5]
	v_mfma_f32_16x16x32_bf16 v[2:5], v[154:157], v[186:189], v[2:5]
	v_mfma_f32_16x16x32_bf16 v[6:9], v[146:149], v[186:189], v[6:9]
	v_mfma_f32_16x16x32_bf16 v[6:9], v[150:153], v[220:223], v[6:9]
	v_mfma_f32_16x16x32_bf16 v[22:25], v[150:153], v[182:185], v[22:25]
	v_mfma_f32_16x16x32_bf16 v[22:25], v[146:149], v[178:181], v[22:25]
	v_mfma_f32_16x16x32_bf16 v[38:41], v[146:149], v[170:173], v[38:41]
	v_mfma_f32_16x16x32_bf16 v[38:41], v[150:153], v[174:177], v[38:41]
	v_mfma_f32_16x16x32_bf16 v[54:57], v[150:153], v[166:169], v[54:57]
	s_barrier
	v_mfma_f32_16x16x32_bf16 v[54:57], v[146:149], v[162:165], v[54:57]
	s_setprio 0
	s_add_i32 s44, 0, 0x18000
	s_add_i32 s45, 0, 0x1c000
	s_add_u32 s12, s50, 0x2b0000
	s_addc_u32 s13, s51, 0
	v_add_u32_e32 v142, s44, v193
	v_add_u32_e32 v158, s45, v193
	ds_read_b128 v[130:133], v142
	ds_read_b128 v[134:137], v142 offset:1024
	ds_read_b128 v[138:141], v142 offset:2048
	ds_read_b128 v[142:145], v142 offset:3072
	ds_read_b128 v[146:149], v158
	ds_read_b128 v[150:153], v158 offset:1024
	ds_read_b128 v[154:157], v158 offset:2048
	ds_read_b128 v[158:161], v158 offset:3072
	ds_read_b128 v[162:165], v197 offset:32768
	ds_read_b128 v[166:169], v197 offset:33792
	ds_read_b128 v[170:173], v197 offset:34816
	ds_read_b128 v[174:177], v197 offset:35840
	ds_read_b128 v[178:181], v197 offset:36864
	ds_read_b128 v[182:185], v197 offset:37888
	ds_read_b128 v[186:189], v197 offset:38912
	ds_read_b128 v[220:223], v197 offset:39936
	s_mov_b32 m0, s58
	s_nop 0
	global_load_lds_dwordx4 v210, s[12:13]
	s_mov_b32 m0, s59
	s_nop 0
	global_load_lds_dwordx4 v212, s[12:13]
	s_waitcnt vmcnt(8)
	s_waitcnt lgkmcnt(0)
	s_barrier
	s_waitcnt lgkmcnt(0)
	v_mfma_f32_16x16x32_bf16 v[126:129], v[130:133], v[162:165], v[126:129]
	v_mfma_f32_16x16x32_bf16 v[126:129], v[134:137], v[166:169], v[126:129]
	s_setprio 1
	v_mfma_f32_16x16x32_bf16 v[110:113], v[134:137], v[174:177], v[110:113]
	v_mfma_f32_16x16x32_bf16 v[110:113], v[130:133], v[170:173], v[110:113]
	v_mfma_f32_16x16x32_bf16 v[98:101], v[130:133], v[178:181], v[98:101]
	v_mfma_f32_16x16x32_bf16 v[98:101], v[134:137], v[182:185], v[98:101]
	v_mfma_f32_16x16x32_bf16 v[82:85], v[134:137], v[220:223], v[82:85]
	v_mfma_f32_16x16x32_bf16 v[82:85], v[130:133], v[186:189], v[82:85]
	v_mfma_f32_16x16x32_bf16 v[74:77], v[138:141], v[186:189], v[74:77]
	v_mfma_f32_16x16x32_bf16 v[74:77], v[142:145], v[220:223], v[74:77]
	v_mfma_f32_16x16x32_bf16 v[90:93], v[142:145], v[182:185], v[90:93]
	v_mfma_f32_16x16x32_bf16 v[90:93], v[138:141], v[178:181], v[90:93]
	v_mfma_f32_16x16x32_bf16 v[106:109], v[138:141], v[170:173], v[106:109]
	v_mfma_f32_16x16x32_bf16 v[106:109], v[142:145], v[174:177], v[106:109]
	v_mfma_f32_16x16x32_bf16 v[122:125], v[142:145], v[166:169], v[122:125]
	v_mfma_f32_16x16x32_bf16 v[122:125], v[138:141], v[162:165], v[122:125]
	v_mfma_f32_16x16x32_bf16 v[114:117], v[154:157], v[162:165], v[114:117]
	v_mfma_f32_16x16x32_bf16 v[114:117], v[158:161], v[166:169], v[114:117]
	v_mfma_f32_16x16x32_bf16 v[94:97], v[158:161], v[174:177], v[94:97]
	v_mfma_f32_16x16x32_bf16 v[94:97], v[154:157], v[170:173], v[94:97]
	v_mfma_f32_16x16x32_bf16 v[78:81], v[154:157], v[178:181], v[78:81]
	v_mfma_f32_16x16x32_bf16 v[78:81], v[158:161], v[182:185], v[78:81]
	v_mfma_f32_16x16x32_bf16 v[66:69], v[158:161], v[220:223], v[66:69]
	v_mfma_f32_16x16x32_bf16 v[66:69], v[154:157], v[186:189], v[66:69]
	v_mfma_f32_16x16x32_bf16 v[70:73], v[146:149], v[186:189], v[70:73]
	v_mfma_f32_16x16x32_bf16 v[70:73], v[150:153], v[220:223], v[70:73]
	v_mfma_f32_16x16x32_bf16 v[86:89], v[150:153], v[182:185], v[86:89]
	v_mfma_f32_16x16x32_bf16 v[86:89], v[146:149], v[178:181], v[86:89]
	v_mfma_f32_16x16x32_bf16 v[102:105], v[146:149], v[170:173], v[102:105]
	v_mfma_f32_16x16x32_bf16 v[102:105], v[150:153], v[174:177], v[102:105]
	v_mfma_f32_16x16x32_bf16 v[118:121], v[150:153], v[166:169], v[118:121]
	s_barrier
	v_mfma_f32_16x16x32_bf16 v[118:121], v[146:149], v[162:165], v[118:121]
	s_setprio 0
	s_add_i32 s12, s44, s29
	ds_read_b128 v[162:165], v197 offset:49152
	ds_read_b128 v[166:169], v197 offset:50176
	ds_read_b128 v[170:173], v197 offset:51200
	ds_read_b128 v[174:177], v197 offset:52224
	ds_read_b128 v[178:181], v197 offset:53248
	ds_read_b128 v[182:185], v197 offset:54272
	ds_read_b128 v[186:189], v197 offset:55296
	ds_read_b128 v[220:223], v197 offset:56320
	s_mov_b32 m0, s12
	s_nop 0
	global_load_lds_dwordx4 v224, s[48:49]
	s_add_i32 m0, s12, 0x2000
	s_add_u32 s12, s48, 0x2b0080
	s_addc_u32 s13, s49, 0
	s_add_i32 s44, s45, s29
	global_load_lds_dwordx4 v227, s[48:49]
	s_mov_b32 m0, s44
	s_nop 0
	global_load_lds_dwordx4 v190, s[12:13]
	s_add_i32 m0, s44, 0x2000
	s_nop 0
	global_load_lds_dwordx4 v214, s[12:13]
	s_mov_b32 m0, s60
	s_nop 0
	global_load_lds_dwordx4 v225, s[50:51]
	s_mov_b32 m0, s62
	s_nop 0
	global_load_lds_dwordx4 v226, s[50:51]
	s_waitcnt vmcnt(8)
	s_waitcnt lgkmcnt(0)
	s_barrier
	s_waitcnt lgkmcnt(0)
	v_mfma_f32_16x16x32_bf16 v[62:65], v[130:133], v[162:165], v[62:65]
	v_mfma_f32_16x16x32_bf16 v[62:65], v[134:137], v[166:169], v[62:65]
	s_setprio 1
	v_mfma_f32_16x16x32_bf16 v[50:53], v[134:137], v[174:177], v[50:53]
	v_mfma_f32_16x16x32_bf16 v[50:53], v[130:133], v[170:173], v[50:53]
	v_mfma_f32_16x16x32_bf16 v[34:37], v[130:133], v[178:181], v[34:37]
	v_mfma_f32_16x16x32_bf16 v[34:37], v[134:137], v[182:185], v[34:37]
	v_mfma_f32_16x16x32_bf16 v[18:21], v[134:137], v[220:223], v[18:21]
	v_mfma_f32_16x16x32_bf16 v[18:21], v[130:133], v[186:189], v[18:21]
	v_mfma_f32_16x16x32_bf16 v[10:13], v[138:141], v[186:189], v[10:13]
	v_mfma_f32_16x16x32_bf16 v[10:13], v[142:145], v[220:223], v[10:13]
	v_mfma_f32_16x16x32_bf16 v[26:29], v[142:145], v[182:185], v[26:29]
	v_mfma_f32_16x16x32_bf16 v[26:29], v[138:141], v[178:181], v[26:29]
	v_mfma_f32_16x16x32_bf16 v[42:45], v[138:141], v[170:173], v[42:45]
	v_mfma_f32_16x16x32_bf16 v[42:45], v[142:145], v[174:177], v[42:45]
	v_mfma_f32_16x16x32_bf16 v[58:61], v[142:145], v[166:169], v[58:61]
	v_mfma_f32_16x16x32_bf16 v[58:61], v[138:141], v[162:165], v[58:61]
	v_mfma_f32_16x16x32_bf16 v[46:49], v[154:157], v[162:165], v[46:49]
	v_mfma_f32_16x16x32_bf16 v[46:49], v[158:161], v[166:169], v[46:49]
	v_mfma_f32_16x16x32_bf16 v[30:33], v[158:161], v[174:177], v[30:33]
	v_mfma_f32_16x16x32_bf16 v[30:33], v[154:157], v[170:173], v[30:33]
	v_mfma_f32_16x16x32_bf16 v[14:17], v[154:157], v[178:181], v[14:17]
	v_mfma_f32_16x16x32_bf16 v[14:17], v[158:161], v[182:185], v[14:17]
	v_mfma_f32_16x16x32_bf16 v[2:5], v[158:161], v[220:223], v[2:5]
	v_mfma_f32_16x16x32_bf16 v[2:5], v[154:157], v[186:189], v[2:5]
	v_mfma_f32_16x16x32_bf16 v[6:9], v[146:149], v[186:189], v[6:9]
	v_mfma_f32_16x16x32_bf16 v[6:9], v[150:153], v[220:223], v[6:9]
	v_mfma_f32_16x16x32_bf16 v[22:25], v[150:153], v[182:185], v[22:25]
	v_mfma_f32_16x16x32_bf16 v[22:25], v[146:149], v[178:181], v[22:25]
	v_mfma_f32_16x16x32_bf16 v[38:41], v[146:149], v[170:173], v[38:41]
	v_mfma_f32_16x16x32_bf16 v[38:41], v[150:153], v[174:177], v[38:41]
	v_mfma_f32_16x16x32_bf16 v[54:57], v[150:153], v[166:169], v[54:57]
	s_barrier
	v_mfma_f32_16x16x32_bf16 v[54:57], v[146:149], v[162:165], v[54:57]
	s_setprio 0
	s_add_i32 s70, s70, 2
	s_add_u32 s61, s61, 0x100
	s_addc_u32 s69, s69, 0
	s_cmpk_gt_u32 s70, 0xa9
	s_mov_b64 s[44:45], s[46:47]
	s_cbranch_scc0 .LBB0_983
	s_and_b64 vcc, exec, s[30:31]
	s_cbranch_vccz .LBB0_986
	s_barrier
